# plus static s_setprio 1 for waves 4-7 inside the FoX tile loops
# speedup vs baseline: 1.0020x; 1.0020x over previous
.LBB0_625:
	s_setprio 0
	v_mov_b32_e32 v0, v196
	v_nop
	v_nop
	v_permlane32_swap_b32 v196, v0
	s_mulk_i32 s22, 0x110
	v_add_f32_e32 v146, v196, v0
	v_ashrrev_i32_e32 v0, 31, v147
	v_lshrrev_b32_e32 v0, 28, v0
	v_add_u32_e32 v0, v147, v0
	s_waitcnt vmcnt(0)
	v_ashrrev_i32_e32 v144, 4, v0
	v_and_b32_e32 v0, -16, v0
	v_sub_u32_e32 v148, v147, v0
	v_lshlrev_b32_e32 v68, 3, v148
	v_ashrrev_i32_e32 v69, 31, v68
	v_add_u32_e32 v0, 64, v147
	v_lshlrev_b64 v[140:141], 1, v[68:69]
	v_ashrrev_i32_e32 v68, 31, v0
	v_lshrrev_b32_e32 v68, 28, v68
	v_ashrrev_i32_e32 v145, 31, v144
	v_add_u32_e32 v68, v0, v68
	v_lshl_add_u64 v[138:139], s[4:5], 0, v[144:145]
	v_ashrrev_i32_e32 v142, 4, v68
	v_lshlrev_b64 v[66:67], 14, v[138:139]
	v_and_b32_e32 v68, -16, v68
	v_ashrrev_i32_e32 v143, 31, v142
	v_lshl_add_u64 v[66:67], s[12:13], 0, v[66:67]
	v_sub_u32_e32 v145, v0, v68
	v_lshl_add_u64 v[132:133], s[4:5], 0, v[142:143]
	v_lshl_add_u64 v[66:67], v[66:67], 0, s[16:17]
	v_lshlrev_b64 v[68:69], 14, v[132:133]
	v_lshlrev_b32_e32 v70, 3, v145
	v_lshl_add_u64 v[66:67], v[66:67], 0, v[140:141]
	v_lshl_add_u64 v[68:69], s[12:13], 0, v[68:69]
	v_ashrrev_i32_e32 v71, 31, v70
	v_add_co_u32_e32 v66, vcc, s48, v66
	v_lshl_add_u64 v[68:69], v[68:69], 0, s[16:17]
	v_lshlrev_b64 v[134:135], 1, v[70:71]
	v_addc_co_u32_e32 v67, vcc, 0, v67, vcc
	v_lshl_add_u64 v[68:69], v[68:69], 0, v[134:135]
	v_add_co_u32_e32 v68, vcc, s48, v68
	v_add_u32_e32 v0, 0x80, v147
	s_nop 0
	v_addc_co_u32_e32 v69, vcc, 0, v69, vcc
	global_load_dwordx4 v[94:97], v[66:67], off
	global_load_dwordx4 v[90:93], v[68:69], off
	v_ashrrev_i32_e32 v66, 31, v0
	v_lshrrev_b32_e32 v66, 28, v66
	v_add_u32_e32 v66, v0, v66
	v_ashrrev_i32_e32 v136, 4, v66
	v_and_b32_e32 v66, -16, v66
	v_sub_u32_e32 v143, v0, v66
	v_lshlrev_b32_e32 v68, 3, v143
	v_ashrrev_i32_e32 v69, 31, v68
	v_add_u32_e32 v0, 0xc0, v147
	v_lshlrev_b64 v[128:129], 1, v[68:69]
	v_ashrrev_i32_e32 v68, 31, v0
	v_lshrrev_b32_e32 v68, 28, v68
	v_ashrrev_i32_e32 v137, 31, v136
	v_add_u32_e32 v68, v0, v68
	v_lshl_add_u64 v[126:127], s[4:5], 0, v[136:137]
	v_ashrrev_i32_e32 v130, 4, v68
	v_lshlrev_b64 v[66:67], 14, v[126:127]
	v_and_b32_e32 v68, -16, v68
	v_ashrrev_i32_e32 v131, 31, v130
	v_lshl_add_u64 v[66:67], s[12:13], 0, v[66:67]
	v_sub_u32_e32 v137, v0, v68
	v_lshl_add_u64 v[120:121], s[4:5], 0, v[130:131]
	v_lshl_add_u64 v[66:67], v[66:67], 0, s[16:17]
	v_lshlrev_b64 v[68:69], 14, v[120:121]
	v_lshlrev_b32_e32 v70, 3, v137
	v_lshl_add_u64 v[66:67], v[66:67], 0, v[128:129]
	v_lshl_add_u64 v[68:69], s[12:13], 0, v[68:69]
	v_ashrrev_i32_e32 v71, 31, v70
	v_add_co_u32_e32 v66, vcc, s48, v66
	v_lshl_add_u64 v[68:69], v[68:69], 0, s[16:17]
	v_lshlrev_b64 v[122:123], 1, v[70:71]
	v_addc_co_u32_e32 v67, vcc, 0, v67, vcc
	v_lshl_add_u64 v[68:69], v[68:69], 0, v[122:123]
	v_add_co_u32_e32 v68, vcc, s48, v68
	v_add_u32_e32 v0, 0x100, v147
	s_nop 0
	v_addc_co_u32_e32 v69, vcc, 0, v69, vcc
	global_load_dwordx4 v[86:89], v[66:67], off
	global_load_dwordx4 v[82:85], v[68:69], off
	v_ashrrev_i32_e32 v66, 31, v0
	v_lshrrev_b32_e32 v66, 28, v66
	v_add_u32_e32 v66, v0, v66
	v_ashrrev_i32_e32 v124, 4, v66
	v_and_b32_e32 v66, -16, v66
	v_sub_u32_e32 v131, v0, v66
	v_lshlrev_b32_e32 v68, 3, v131
	v_ashrrev_i32_e32 v69, 31, v68
	v_add_u32_e32 v0, 0x140, v147
	v_lshlrev_b64 v[116:117], 1, v[68:69]
	v_ashrrev_i32_e32 v68, 31, v0
	v_lshrrev_b32_e32 v68, 28, v68
	v_ashrrev_i32_e32 v125, 31, v124
	v_add_u32_e32 v68, v0, v68
	v_lshl_add_u64 v[114:115], s[4:5], 0, v[124:125]
	v_ashrrev_i32_e32 v118, 4, v68
	v_lshlrev_b64 v[66:67], 14, v[114:115]
	v_and_b32_e32 v68, -16, v68
	v_ashrrev_i32_e32 v119, 31, v118
	v_lshl_add_u64 v[66:67], s[12:13], 0, v[66:67]
	v_sub_u32_e32 v125, v0, v68
	v_lshl_add_u64 v[108:109], s[4:5], 0, v[118:119]
	v_lshl_add_u64 v[66:67], v[66:67], 0, s[16:17]
	v_lshlrev_b64 v[68:69], 14, v[108:109]
	v_lshlrev_b32_e32 v70, 3, v125
	v_lshl_add_u64 v[66:67], v[66:67], 0, v[116:117]
	v_lshl_add_u64 v[68:69], s[12:13], 0, v[68:69]
	v_ashrrev_i32_e32 v71, 31, v70
	v_add_co_u32_e32 v66, vcc, s48, v66
	v_lshl_add_u64 v[68:69], v[68:69], 0, s[16:17]
	v_lshlrev_b64 v[110:111], 1, v[70:71]
	v_addc_co_u32_e32 v67, vcc, 0, v67, vcc
	v_lshl_add_u64 v[68:69], v[68:69], 0, v[110:111]
	v_add_co_u32_e32 v68, vcc, s48, v68
	v_add_u32_e32 v0, 0x180, v147
	s_nop 0
	v_addc_co_u32_e32 v69, vcc, 0, v69, vcc
	global_load_dwordx4 v[78:81], v[66:67], off
	global_load_dwordx4 v[74:77], v[68:69], off
	v_ashrrev_i32_e32 v66, 31, v0
	v_lshrrev_b32_e32 v66, 28, v66
	v_add_u32_e32 v66, v0, v66
	v_ashrrev_i32_e32 v112, 4, v66
	v_and_b32_e32 v66, -16, v66
	v_sub_u32_e32 v119, v0, v66
	v_lshlrev_b32_e32 v68, 3, v119
	v_ashrrev_i32_e32 v69, 31, v68
	v_add_u32_e32 v0, 0x1c0, v147
	v_lshlrev_b64 v[104:105], 1, v[68:69]
	v_ashrrev_i32_e32 v68, 31, v0
	v_lshrrev_b32_e32 v68, 28, v68
	v_ashrrev_i32_e32 v113, 31, v112
	v_add_u32_e32 v68, v0, v68
	v_lshl_add_u64 v[102:103], s[4:5], 0, v[112:113]
	v_ashrrev_i32_e32 v106, 4, v68
	v_lshlrev_b64 v[66:67], 14, v[102:103]
	v_and_b32_e32 v68, -16, v68
	v_ashrrev_i32_e32 v107, 31, v106
	v_lshl_add_u64 v[66:67], s[12:13], 0, v[66:67]
	v_sub_u32_e32 v0, v0, v68
	v_lshl_add_u64 v[98:99], s[4:5], 0, v[106:107]
	v_lshl_add_u64 v[66:67], v[66:67], 0, s[16:17]
	v_lshlrev_b64 v[68:69], 14, v[98:99]
	v_lshlrev_b32_e32 v70, 3, v0
	v_div_scale_f32 v107, s[4:5], v146, v146, 1.0
	v_lshl_add_u64 v[66:67], v[66:67], 0, v[104:105]
	v_lshl_add_u64 v[68:69], s[12:13], 0, v[68:69]
	v_ashrrev_i32_e32 v71, 31, v70
	v_rcp_f32_e32 v113, v107
	v_add_co_u32_e32 v66, vcc, s48, v66
	v_lshl_add_u64 v[68:69], v[68:69], 0, s[16:17]
	v_lshlrev_b64 v[100:101], 1, v[70:71]
	v_addc_co_u32_e32 v67, vcc, 0, v67, vcc
	v_lshl_add_u64 v[68:69], v[68:69], 0, v[100:101]
	v_add_co_u32_e32 v68, vcc, s48, v68
	v_fma_f32 v149, -v107, v113, 1.0
	s_nop 0
	v_addc_co_u32_e32 v69, vcc, 0, v69, vcc
	v_fmac_f32_e32 v113, v149, v113
	v_div_scale_f32 v149, vcc, 1.0, v146, 1.0
	v_mul_f32_e32 v150, v149, v113
	v_fma_f32 v151, -v107, v150, v149
	v_fmac_f32_e32 v150, v151, v113
	v_fma_f32 v107, -v107, v150, v149
	v_div_fmas_f32 v107, v107, v113, v150
	v_div_fixup_f32 v146, v107, v146, 1.0
	v_pk_mul_f32 v[50:51], v[50:51], v[146:147] op_sel_hi:[1,0]
	v_pk_mul_f32 v[52:53], v[52:53], v[146:147] op_sel_hi:[1,0]
	v_and_b32_e32 v107, 31, v147
	v_cvt_pk_bf16_f32 v50, v50, v51
	v_cvt_pk_bf16_f32 v51, v52, v53
	v_ashrrev_i32_e32 v52, 2, v147
	v_pk_mul_f32 v[2:3], v[2:3], v[146:147] op_sel_hi:[1,0]
	v_pk_mul_f32 v[4:5], v[4:5], v[146:147] op_sel_hi:[1,0]
	s_add_i32 s4, s22, 0
	v_mul_u32_u24_e32 v107, 0x110, v107
	v_and_b32_e32 v52, -8, v52
	v_cvt_pk_bf16_f32 v2, v2, v3
	v_cvt_pk_bf16_f32 v3, v4, v5
	v_pk_mul_f32 v[4:5], v[6:7], v[146:147] op_sel_hi:[1,0]
	v_pk_mul_f32 v[6:7], v[8:9], v[146:147] op_sel_hi:[1,0]
	v_add3_u32 v107, s4, v107, v52
	v_cvt_pk_bf16_f32 v4, v4, v5
	v_cvt_pk_bf16_f32 v5, v6, v7
	global_load_dwordx4 v[70:73], v[66:67], off
	s_nop 0
	global_load_dwordx4 v[66:69], v[68:69], off
	v_pk_mul_f32 v[34:35], v[34:35], v[146:147] op_sel_hi:[1,0]
	v_pk_mul_f32 v[36:37], v[36:37], v[146:147] op_sel_hi:[1,0]
	v_pk_mul_f32 v[18:19], v[18:19], v[146:147] op_sel_hi:[1,0]
	v_pk_mul_f32 v[20:21], v[20:21], v[146:147] op_sel_hi:[1,0]
	ds_write2_b64 v107, v[2:3], v[4:5] offset0:24 offset1:26
	v_pk_mul_f32 v[2:3], v[10:11], v[146:147] op_sel_hi:[1,0]
	v_pk_mul_f32 v[4:5], v[12:13], v[146:147] op_sel_hi:[1,0]
	v_pk_mul_f32 v[52:53], v[54:55], v[146:147] op_sel_hi:[1,0]
	v_pk_mul_f32 v[54:55], v[56:57], v[146:147] op_sel_hi:[1,0]
	v_cvt_pk_bf16_f32 v34, v34, v35
	v_cvt_pk_bf16_f32 v35, v36, v37
	v_pk_mul_f32 v[36:37], v[38:39], v[146:147] op_sel_hi:[1,0]
	v_pk_mul_f32 v[38:39], v[40:41], v[146:147] op_sel_hi:[1,0]
	v_cvt_pk_bf16_f32 v18, v18, v19
	v_cvt_pk_bf16_f32 v19, v20, v21
	v_pk_mul_f32 v[20:21], v[22:23], v[146:147] op_sel_hi:[1,0]
	v_pk_mul_f32 v[22:23], v[24:25], v[146:147] op_sel_hi:[1,0]
	v_cvt_pk_bf16_f32 v2, v2, v3
	v_cvt_pk_bf16_f32 v3, v4, v5
	v_pk_mul_f32 v[4:5], v[14:15], v[146:147] op_sel_hi:[1,0]
	v_pk_mul_f32 v[6:7], v[16:17], v[146:147] op_sel_hi:[1,0]
	v_cvt_pk_bf16_f32 v52, v52, v53
	v_cvt_pk_bf16_f32 v53, v54, v55
	v_cvt_pk_bf16_f32 v36, v36, v37
	v_cvt_pk_bf16_f32 v37, v38, v39
	v_cvt_pk_bf16_f32 v20, v20, v21
	v_cvt_pk_bf16_f32 v21, v22, v23
	v_cvt_pk_bf16_f32 v4, v4, v5
	v_cvt_pk_bf16_f32 v5, v6, v7
	ds_write2_b64 v107, v[50:51], v[52:53] offset1:2
	v_pk_mul_f32 v[50:51], v[58:59], v[146:147] op_sel_hi:[1,0]
	v_pk_mul_f32 v[52:53], v[60:61], v[146:147] op_sel_hi:[1,0]
	ds_write2_b64 v107, v[34:35], v[36:37] offset0:8 offset1:10
	v_pk_mul_f32 v[34:35], v[42:43], v[146:147] op_sel_hi:[1,0]
	v_pk_mul_f32 v[36:37], v[44:45], v[146:147] op_sel_hi:[1,0]
	ds_write2_b64 v107, v[18:19], v[20:21] offset0:16 offset1:18
	v_pk_mul_f32 v[18:19], v[26:27], v[146:147] op_sel_hi:[1,0]
	v_pk_mul_f32 v[20:21], v[28:29], v[146:147] op_sel_hi:[1,0]
	ds_write2_b64 v107, v[2:3], v[4:5] offset0:28 offset1:30
	v_mul_lo_u32 v2, v144, s45
	v_lshlrev_b32_e32 v3, 4, v148
	s_waitcnt vmcnt(7)
	v_lshlrev_b32_e32 v10, 16, v94
	v_cvt_pk_bf16_f32 v50, v50, v51
	v_cvt_pk_bf16_f32 v51, v52, v53
	v_pk_mul_f32 v[52:53], v[62:63], v[146:147] op_sel_hi:[1,0]
	v_pk_mul_f32 v[54:55], v[64:65], v[146:147] op_sel_hi:[1,0]
	v_cvt_pk_bf16_f32 v34, v34, v35
	v_cvt_pk_bf16_f32 v35, v36, v37
	v_pk_mul_f32 v[36:37], v[46:47], v[146:147] op_sel_hi:[1,0]
	v_pk_mul_f32 v[38:39], v[48:49], v[146:147] op_sel_hi:[1,0]
	v_cvt_pk_bf16_f32 v18, v18, v19
	v_cvt_pk_bf16_f32 v19, v20, v21
	v_pk_mul_f32 v[20:21], v[30:31], v[146:147] op_sel_hi:[1,0]
	v_pk_mul_f32 v[22:23], v[32:33], v[146:147] op_sel_hi:[1,0]
	v_add3_u32 v2, s4, v2, v3
	v_and_b32_e32 v13, 0xffff0000, v94
	v_mul_f32_e32 v3, 0xbfb8aa3b, v10
	v_cvt_pk_bf16_f32 v52, v52, v53
	v_cvt_pk_bf16_f32 v53, v54, v55
	v_cvt_pk_bf16_f32 v36, v36, v37
	v_cvt_pk_bf16_f32 v37, v38, v39
	v_cvt_pk_bf16_f32 v20, v20, v21
	v_cvt_pk_bf16_f32 v21, v22, v23
	v_exp_f32_e32 v6, v3
	v_mul_f32_e32 v3, 0xbfb8aa3b, v13
	ds_write2_b64 v107, v[50:51], v[52:53] offset0:4 offset1:6
	ds_write2_b64 v107, v[34:35], v[36:37] offset0:12 offset1:14
	ds_write2_b64 v107, v[18:19], v[20:21] offset0:20 offset1:22
	v_exp_f32_e32 v7, v3
	s_waitcnt lgkmcnt(0)
	ds_read_b128 v[2:5], v2
	v_add_f32_e32 v6, 1.0, v6
	v_rcp_f32_e32 v14, v6
	v_add_f32_e32 v6, 1.0, v7
	v_rcp_f32_e32 v15, v6
	v_mul_lo_u32 v6, v142, s45
	v_lshlrev_b32_e32 v7, 4, v145
	v_add3_u32 v6, s4, v6, v7
	ds_read_b128 v[6:9], v6
	s_waitcnt lgkmcnt(1)
	v_and_b32_e32 v11, 0xffff0000, v2
	v_lshlrev_b32_e32 v12, 16, v2
	v_pk_mul_f32 v[10:11], v[12:13], v[10:11]
	v_lshlrev_b32_e32 v12, 16, v95
	v_pk_mul_f32 v[10:11], v[14:15], v[10:11]
	v_and_b32_e32 v15, 0xffff0000, v95
	v_mul_f32_e32 v2, 0xbfb8aa3b, v12
	v_exp_f32_e32 v13, v2
	v_mul_f32_e32 v2, 0xbfb8aa3b, v15
	v_exp_f32_e32 v14, v2
	v_cvt_pk_bf16_f32 v2, v10, v11
	v_add_f32_e32 v10, 1.0, v13
	v_rcp_f32_e32 v10, v10
	v_add_f32_e32 v11, 1.0, v14
	v_rcp_f32_e32 v11, v11
	v_and_b32_e32 v13, 0xffff0000, v3
	v_lshlrev_b32_e32 v14, 16, v3
	v_pk_mul_f32 v[12:13], v[14:15], v[12:13]
	v_and_b32_e32 v15, 0xffff0000, v96
	v_pk_mul_f32 v[10:11], v[10:11], v[12:13]
	v_lshlrev_b32_e32 v12, 16, v96
	v_mul_f32_e32 v3, 0xbfb8aa3b, v12
	v_exp_f32_e32 v13, v3
	v_mul_f32_e32 v3, 0xbfb8aa3b, v15
	v_exp_f32_e32 v14, v3
	v_cvt_pk_bf16_f32 v3, v10, v11
	v_add_f32_e32 v10, 1.0, v13
	v_rcp_f32_e32 v10, v10
	v_add_f32_e32 v11, 1.0, v14
	v_rcp_f32_e32 v11, v11
	v_and_b32_e32 v13, 0xffff0000, v4
	v_lshlrev_b32_e32 v14, 16, v4
	v_pk_mul_f32 v[12:13], v[14:15], v[12:13]
	v_and_b32_e32 v15, 0xffff0000, v97
	v_pk_mul_f32 v[10:11], v[10:11], v[12:13]
	v_lshlrev_b32_e32 v12, 16, v97
	v_mul_f32_e32 v4, 0xbfb8aa3b, v12
	v_exp_f32_e32 v13, v4
	v_mul_f32_e32 v4, 0xbfb8aa3b, v15
	v_exp_f32_e32 v14, v4
	v_cvt_pk_bf16_f32 v4, v10, v11
	v_add_f32_e32 v10, 1.0, v13
	v_rcp_f32_e32 v10, v10
	v_add_f32_e32 v11, 1.0, v14
	v_rcp_f32_e32 v11, v11
	v_and_b32_e32 v13, 0xffff0000, v5
	v_lshlrev_b32_e32 v14, 16, v5
	v_pk_mul_f32 v[12:13], v[14:15], v[12:13]
	s_waitcnt vmcnt(6)
	v_and_b32_e32 v15, 0xffff0000, v90
	v_pk_mul_f32 v[10:11], v[10:11], v[12:13]
	v_lshlrev_b32_e32 v12, 16, v90
	v_mul_f32_e32 v13, 0xbfb8aa3b, v12
	v_mul_f32_e32 v14, 0xbfb8aa3b, v15
	v_exp_f32_e32 v13, v13
	v_exp_f32_e32 v14, v14
	v_cvt_pk_bf16_f32 v5, v10, v11
	v_lshlrev_b64 v[10:11], 12, v[138:139]
	v_lshl_add_u64 v[10:11], s[0:1], 0, v[10:11]
	v_lshl_add_u64 v[10:11], v[10:11], 0, v[140:141]
	global_store_dwordx4 v[10:11], v[2:5], off
	v_and_b32_e32 v11, 0xffff0000, v91
	s_waitcnt lgkmcnt(0)
	v_lshlrev_b32_e32 v10, 16, v7
	v_add_f32_e32 v2, 1.0, v13
	v_add_f32_e32 v3, 1.0, v14
	v_rcp_f32_e32 v2, v2
	v_rcp_f32_e32 v3, v3
	v_and_b32_e32 v13, 0xffff0000, v6
	v_lshlrev_b32_e32 v14, 16, v6
	v_pk_mul_f32 v[4:5], v[14:15], v[12:13]
	v_mul_f32_e32 v6, 0xbfb8aa3b, v11
	v_pk_mul_f32 v[2:3], v[2:3], v[4:5]
	v_lshlrev_b32_e32 v4, 16, v91
	v_mul_f32_e32 v5, 0xbfb8aa3b, v4
	v_exp_f32_e32 v5, v5
	v_exp_f32_e32 v6, v6
	v_cvt_pk_bf16_f32 v2, v2, v3
	v_lshlrev_b32_e32 v0, 4, v0
	v_add_f32_e32 v3, 1.0, v5
	v_rcp_f32_e32 v12, v3
	v_add_f32_e32 v3, 1.0, v6
	v_and_b32_e32 v5, 0xffff0000, v7
	v_lshlrev_b32_e32 v6, 16, v92
	v_rcp_f32_e32 v13, v3
	v_pk_mul_f32 v[4:5], v[10:11], v[4:5]
	v_and_b32_e32 v11, 0xffff0000, v92
	v_mul_f32_e32 v3, 0xbfb8aa3b, v6
	v_exp_f32_e32 v7, v3
	v_mul_f32_e32 v3, 0xbfb8aa3b, v11
	v_exp_f32_e32 v10, v3
	v_pk_mul_f32 v[4:5], v[12:13], v[4:5]
	s_add_i32 s88, s88, s58
	v_cvt_pk_bf16_f32 v3, v4, v5
	v_add_f32_e32 v4, 1.0, v7
	v_add_f32_e32 v5, 1.0, v10
	v_rcp_f32_e32 v4, v4
	v_rcp_f32_e32 v5, v5
	v_and_b32_e32 v7, 0xffff0000, v8
	v_lshlrev_b32_e32 v10, 16, v8
	v_pk_mul_f32 v[6:7], v[10:11], v[6:7]
	v_and_b32_e32 v11, 0xffff0000, v93
	v_pk_mul_f32 v[4:5], v[4:5], v[6:7]
	v_lshlrev_b32_e32 v6, 16, v93
	v_mul_f32_e32 v7, 0xbfb8aa3b, v6
	v_exp_f32_e32 v7, v7
	v_mul_f32_e32 v8, 0xbfb8aa3b, v11
	v_exp_f32_e32 v8, v8
	v_cvt_pk_bf16_f32 v4, v4, v5
	v_add_f32_e32 v5, 1.0, v7
	v_rcp_f32_e32 v12, v5
	v_add_f32_e32 v5, 1.0, v8
	v_rcp_f32_e32 v13, v5
	v_and_b32_e32 v7, 0xffff0000, v9
	v_lshlrev_b32_e32 v10, 16, v9
	v_pk_mul_f32 v[6:7], v[10:11], v[6:7]
	s_waitcnt vmcnt(6)
	v_lshlrev_b32_e32 v10, 16, v86
	v_pk_mul_f32 v[6:7], v[12:13], v[6:7]
	v_and_b32_e32 v13, 0xffff0000, v86
	v_cvt_pk_bf16_f32 v5, v6, v7
	v_lshlrev_b64 v[6:7], 12, v[132:133]
	v_lshl_add_u64 v[6:7], s[0:1], 0, v[6:7]
	v_lshl_add_u64 v[6:7], v[6:7], 0, v[134:135]
	global_store_dwordx4 v[6:7], v[2:5], off
	s_add_i32 s49, s49, s58
	s_cmpk_lt_i32 s88, 0x200
	v_mul_lo_u32 v2, v136, s45
	v_lshlrev_b32_e32 v3, 4, v143
	v_add3_u32 v2, s4, v2, v3
	v_mul_f32_e32 v3, 0xbfb8aa3b, v10
	v_exp_f32_e32 v6, v3
	v_mul_f32_e32 v3, 0xbfb8aa3b, v13
	v_exp_f32_e32 v7, v3
	ds_read_b128 v[2:5], v2
	v_add_f32_e32 v6, 1.0, v6
	v_rcp_f32_e32 v14, v6
	v_add_f32_e32 v6, 1.0, v7
	v_rcp_f32_e32 v15, v6
	v_mul_lo_u32 v6, v130, s45
	v_lshlrev_b32_e32 v7, 4, v137
	v_add3_u32 v6, s4, v6, v7
	ds_read_b128 v[6:9], v6
	s_waitcnt lgkmcnt(1)
	v_and_b32_e32 v11, 0xffff0000, v2
	v_lshlrev_b32_e32 v12, 16, v2
	v_pk_mul_f32 v[10:11], v[12:13], v[10:11]
	v_lshlrev_b32_e32 v12, 16, v87
	v_pk_mul_f32 v[10:11], v[14:15], v[10:11]
	v_and_b32_e32 v15, 0xffff0000, v87
	v_mul_f32_e32 v2, 0xbfb8aa3b, v12
	v_exp_f32_e32 v13, v2
	v_mul_f32_e32 v2, 0xbfb8aa3b, v15
	v_exp_f32_e32 v14, v2
	v_cvt_pk_bf16_f32 v2, v10, v11
	v_add_f32_e32 v10, 1.0, v13
	v_rcp_f32_e32 v10, v10
	v_add_f32_e32 v11, 1.0, v14
	v_rcp_f32_e32 v11, v11
	v_and_b32_e32 v13, 0xffff0000, v3
	v_lshlrev_b32_e32 v14, 16, v3
	v_pk_mul_f32 v[12:13], v[14:15], v[12:13]
	v_and_b32_e32 v15, 0xffff0000, v88
	v_pk_mul_f32 v[10:11], v[10:11], v[12:13]
	v_lshlrev_b32_e32 v12, 16, v88
	v_mul_f32_e32 v3, 0xbfb8aa3b, v12
	v_exp_f32_e32 v13, v3
	v_mul_f32_e32 v3, 0xbfb8aa3b, v15
	v_exp_f32_e32 v14, v3
	v_cvt_pk_bf16_f32 v3, v10, v11
	v_add_f32_e32 v10, 1.0, v13
	v_rcp_f32_e32 v10, v10
	v_add_f32_e32 v11, 1.0, v14
	v_rcp_f32_e32 v11, v11
	v_and_b32_e32 v13, 0xffff0000, v4
	v_lshlrev_b32_e32 v14, 16, v4
	v_pk_mul_f32 v[12:13], v[14:15], v[12:13]
	v_and_b32_e32 v15, 0xffff0000, v89
	v_pk_mul_f32 v[10:11], v[10:11], v[12:13]
	v_lshlrev_b32_e32 v12, 16, v89
	v_mul_f32_e32 v4, 0xbfb8aa3b, v12
	v_exp_f32_e32 v13, v4
	v_mul_f32_e32 v4, 0xbfb8aa3b, v15
	v_exp_f32_e32 v14, v4
	v_cvt_pk_bf16_f32 v4, v10, v11
	v_add_f32_e32 v10, 1.0, v13
	v_rcp_f32_e32 v10, v10
	v_add_f32_e32 v11, 1.0, v14
	v_rcp_f32_e32 v11, v11
	v_and_b32_e32 v13, 0xffff0000, v5
	v_lshlrev_b32_e32 v14, 16, v5
	v_pk_mul_f32 v[12:13], v[14:15], v[12:13]
	s_waitcnt vmcnt(6)
	v_and_b32_e32 v15, 0xffff0000, v82
	v_pk_mul_f32 v[10:11], v[10:11], v[12:13]
	v_lshlrev_b32_e32 v12, 16, v82
	v_mul_f32_e32 v13, 0xbfb8aa3b, v12
	v_mul_f32_e32 v14, 0xbfb8aa3b, v15
	v_exp_f32_e32 v13, v13
	v_exp_f32_e32 v14, v14
	v_cvt_pk_bf16_f32 v5, v10, v11
	v_lshlrev_b64 v[10:11], 12, v[126:127]
	v_lshl_add_u64 v[10:11], s[0:1], 0, v[10:11]
	v_lshl_add_u64 v[10:11], v[10:11], 0, v[128:129]
	global_store_dwordx4 v[10:11], v[2:5], off
	v_and_b32_e32 v11, 0xffff0000, v83
	s_waitcnt lgkmcnt(0)
	v_lshlrev_b32_e32 v10, 16, v7
	v_add_f32_e32 v2, 1.0, v13
	v_add_f32_e32 v3, 1.0, v14
	v_rcp_f32_e32 v2, v2
	v_rcp_f32_e32 v3, v3
	v_and_b32_e32 v13, 0xffff0000, v6
	v_lshlrev_b32_e32 v14, 16, v6
	v_pk_mul_f32 v[4:5], v[14:15], v[12:13]
	v_mul_f32_e32 v6, 0xbfb8aa3b, v11
	v_pk_mul_f32 v[2:3], v[2:3], v[4:5]
	v_lshlrev_b32_e32 v4, 16, v83
	v_mul_f32_e32 v5, 0xbfb8aa3b, v4
	v_exp_f32_e32 v5, v5
	v_exp_f32_e32 v6, v6
	v_cvt_pk_bf16_f32 v2, v2, v3
	v_add_f32_e32 v3, 1.0, v5
	v_rcp_f32_e32 v12, v3
	v_add_f32_e32 v3, 1.0, v6
	v_and_b32_e32 v5, 0xffff0000, v7
	v_lshlrev_b32_e32 v6, 16, v84
	v_rcp_f32_e32 v13, v3
	v_pk_mul_f32 v[4:5], v[10:11], v[4:5]
	v_and_b32_e32 v11, 0xffff0000, v84
	v_mul_f32_e32 v3, 0xbfb8aa3b, v6
	v_exp_f32_e32 v7, v3
	v_mul_f32_e32 v3, 0xbfb8aa3b, v11
	v_exp_f32_e32 v10, v3
	v_pk_mul_f32 v[4:5], v[12:13], v[4:5]
	s_nop 0
	v_cvt_pk_bf16_f32 v3, v4, v5
	v_add_f32_e32 v4, 1.0, v7
	v_add_f32_e32 v5, 1.0, v10
	v_rcp_f32_e32 v4, v4
	v_rcp_f32_e32 v5, v5
	v_and_b32_e32 v7, 0xffff0000, v8
	v_lshlrev_b32_e32 v10, 16, v8
	v_pk_mul_f32 v[6:7], v[10:11], v[6:7]
	v_and_b32_e32 v11, 0xffff0000, v85
	v_pk_mul_f32 v[4:5], v[4:5], v[6:7]
	v_lshlrev_b32_e32 v6, 16, v85
	v_mul_f32_e32 v7, 0xbfb8aa3b, v6
	v_exp_f32_e32 v7, v7
	v_mul_f32_e32 v8, 0xbfb8aa3b, v11
	v_exp_f32_e32 v8, v8
	v_cvt_pk_bf16_f32 v4, v4, v5
	v_add_f32_e32 v5, 1.0, v7
	v_rcp_f32_e32 v12, v5
	v_add_f32_e32 v5, 1.0, v8
	v_rcp_f32_e32 v13, v5
	v_and_b32_e32 v7, 0xffff0000, v9
	v_lshlrev_b32_e32 v10, 16, v9
	v_pk_mul_f32 v[6:7], v[10:11], v[6:7]
	s_waitcnt vmcnt(6)
	v_lshlrev_b32_e32 v10, 16, v78
	v_pk_mul_f32 v[6:7], v[12:13], v[6:7]
	v_and_b32_e32 v13, 0xffff0000, v78
	v_cvt_pk_bf16_f32 v5, v6, v7
	v_lshlrev_b64 v[6:7], 12, v[120:121]
	v_lshl_add_u64 v[6:7], s[0:1], 0, v[6:7]
	v_lshl_add_u64 v[6:7], v[6:7], 0, v[122:123]
	global_store_dwordx4 v[6:7], v[2:5], off
	s_nop 1
	v_mul_lo_u32 v2, v124, s45
	v_lshlrev_b32_e32 v3, 4, v131
	v_add3_u32 v2, s4, v2, v3
	v_mul_f32_e32 v3, 0xbfb8aa3b, v10
	v_exp_f32_e32 v6, v3
	v_mul_f32_e32 v3, 0xbfb8aa3b, v13
	v_exp_f32_e32 v7, v3
	ds_read_b128 v[2:5], v2
	v_add_f32_e32 v6, 1.0, v6
	v_rcp_f32_e32 v14, v6
	v_add_f32_e32 v6, 1.0, v7
	v_rcp_f32_e32 v15, v6
	v_mul_lo_u32 v6, v118, s45
	v_lshlrev_b32_e32 v7, 4, v125
	v_add3_u32 v6, s4, v6, v7
	ds_read_b128 v[6:9], v6
	s_waitcnt lgkmcnt(1)
	v_and_b32_e32 v11, 0xffff0000, v2
	v_lshlrev_b32_e32 v12, 16, v2
	v_pk_mul_f32 v[10:11], v[12:13], v[10:11]
	v_lshlrev_b32_e32 v12, 16, v79
	v_pk_mul_f32 v[10:11], v[14:15], v[10:11]
	v_and_b32_e32 v15, 0xffff0000, v79
	v_mul_f32_e32 v2, 0xbfb8aa3b, v12
	v_exp_f32_e32 v13, v2
	v_mul_f32_e32 v2, 0xbfb8aa3b, v15
	v_exp_f32_e32 v14, v2
	v_cvt_pk_bf16_f32 v2, v10, v11
	v_add_f32_e32 v10, 1.0, v13
	v_rcp_f32_e32 v10, v10
	v_add_f32_e32 v11, 1.0, v14
	v_rcp_f32_e32 v11, v11
	v_and_b32_e32 v13, 0xffff0000, v3
	v_lshlrev_b32_e32 v14, 16, v3
	v_pk_mul_f32 v[12:13], v[14:15], v[12:13]
	v_and_b32_e32 v15, 0xffff0000, v80
	v_pk_mul_f32 v[10:11], v[10:11], v[12:13]
	v_lshlrev_b32_e32 v12, 16, v80
	v_mul_f32_e32 v3, 0xbfb8aa3b, v12
	v_exp_f32_e32 v13, v3
	v_mul_f32_e32 v3, 0xbfb8aa3b, v15
	v_exp_f32_e32 v14, v3
	v_cvt_pk_bf16_f32 v3, v10, v11
	v_add_f32_e32 v10, 1.0, v13
	v_rcp_f32_e32 v10, v10
	v_add_f32_e32 v11, 1.0, v14
	v_rcp_f32_e32 v11, v11
	v_and_b32_e32 v13, 0xffff0000, v4
	v_lshlrev_b32_e32 v14, 16, v4
	v_pk_mul_f32 v[12:13], v[14:15], v[12:13]
	v_and_b32_e32 v15, 0xffff0000, v81
	v_pk_mul_f32 v[10:11], v[10:11], v[12:13]
	v_lshlrev_b32_e32 v12, 16, v81
	v_mul_f32_e32 v4, 0xbfb8aa3b, v12
	v_exp_f32_e32 v13, v4
	v_mul_f32_e32 v4, 0xbfb8aa3b, v15
	v_exp_f32_e32 v14, v4
	v_cvt_pk_bf16_f32 v4, v10, v11
	v_add_f32_e32 v10, 1.0, v13
	v_rcp_f32_e32 v10, v10
	v_add_f32_e32 v11, 1.0, v14
	v_rcp_f32_e32 v11, v11
	v_and_b32_e32 v13, 0xffff0000, v5
	v_lshlrev_b32_e32 v14, 16, v5
	v_pk_mul_f32 v[12:13], v[14:15], v[12:13]
	s_waitcnt vmcnt(6)
	v_and_b32_e32 v15, 0xffff0000, v74
	v_pk_mul_f32 v[10:11], v[10:11], v[12:13]
	v_lshlrev_b32_e32 v12, 16, v74
	v_mul_f32_e32 v13, 0xbfb8aa3b, v12
	v_mul_f32_e32 v14, 0xbfb8aa3b, v15
	v_exp_f32_e32 v13, v13
	v_exp_f32_e32 v14, v14
	v_cvt_pk_bf16_f32 v5, v10, v11
	v_lshlrev_b64 v[10:11], 12, v[114:115]
	v_lshl_add_u64 v[10:11], s[0:1], 0, v[10:11]
	v_lshl_add_u64 v[10:11], v[10:11], 0, v[116:117]
	global_store_dwordx4 v[10:11], v[2:5], off
	v_and_b32_e32 v11, 0xffff0000, v75
	s_waitcnt lgkmcnt(0)
	v_lshlrev_b32_e32 v10, 16, v7
	v_add_f32_e32 v2, 1.0, v13
	v_add_f32_e32 v3, 1.0, v14
	v_rcp_f32_e32 v2, v2
	v_rcp_f32_e32 v3, v3
	v_and_b32_e32 v13, 0xffff0000, v6
	v_lshlrev_b32_e32 v14, 16, v6
	v_pk_mul_f32 v[4:5], v[14:15], v[12:13]
	v_mul_f32_e32 v6, 0xbfb8aa3b, v11
	v_pk_mul_f32 v[2:3], v[2:3], v[4:5]
	v_lshlrev_b32_e32 v4, 16, v75
	v_mul_f32_e32 v5, 0xbfb8aa3b, v4
	v_exp_f32_e32 v5, v5
	v_exp_f32_e32 v6, v6
	v_cvt_pk_bf16_f32 v2, v2, v3
	v_add_f32_e32 v3, 1.0, v5
	v_rcp_f32_e32 v12, v3
	v_add_f32_e32 v3, 1.0, v6
	v_and_b32_e32 v5, 0xffff0000, v7
	v_lshlrev_b32_e32 v6, 16, v76
	v_rcp_f32_e32 v13, v3
	v_pk_mul_f32 v[4:5], v[10:11], v[4:5]
	v_and_b32_e32 v11, 0xffff0000, v76
	v_mul_f32_e32 v3, 0xbfb8aa3b, v6
	v_exp_f32_e32 v7, v3
	v_mul_f32_e32 v3, 0xbfb8aa3b, v11
	v_exp_f32_e32 v10, v3
	v_pk_mul_f32 v[4:5], v[12:13], v[4:5]
	s_nop 0
	v_cvt_pk_bf16_f32 v3, v4, v5
	v_add_f32_e32 v4, 1.0, v7
	v_add_f32_e32 v5, 1.0, v10
	v_rcp_f32_e32 v4, v4
	v_rcp_f32_e32 v5, v5
	v_and_b32_e32 v7, 0xffff0000, v8
	v_lshlrev_b32_e32 v10, 16, v8
	v_pk_mul_f32 v[6:7], v[10:11], v[6:7]
	v_and_b32_e32 v11, 0xffff0000, v77
	v_pk_mul_f32 v[4:5], v[4:5], v[6:7]
	v_lshlrev_b32_e32 v6, 16, v77
	v_mul_f32_e32 v7, 0xbfb8aa3b, v6
	v_exp_f32_e32 v7, v7
	v_mul_f32_e32 v8, 0xbfb8aa3b, v11
	v_exp_f32_e32 v8, v8
	v_cvt_pk_bf16_f32 v4, v4, v5
	v_add_f32_e32 v5, 1.0, v7
	v_rcp_f32_e32 v12, v5
	v_add_f32_e32 v5, 1.0, v8
	v_rcp_f32_e32 v13, v5
	v_and_b32_e32 v7, 0xffff0000, v9
	v_lshlrev_b32_e32 v10, 16, v9
	v_pk_mul_f32 v[6:7], v[10:11], v[6:7]
	s_waitcnt vmcnt(6)
	v_lshlrev_b32_e32 v10, 16, v70
	v_pk_mul_f32 v[6:7], v[12:13], v[6:7]
	v_and_b32_e32 v13, 0xffff0000, v70
	v_cvt_pk_bf16_f32 v5, v6, v7
	v_lshlrev_b64 v[6:7], 12, v[108:109]
	v_lshl_add_u64 v[6:7], s[0:1], 0, v[6:7]
	v_lshl_add_u64 v[6:7], v[6:7], 0, v[110:111]
	global_store_dwordx4 v[6:7], v[2:5], off
	s_nop 1
	v_mul_lo_u32 v2, v112, s45
	v_lshlrev_b32_e32 v3, 4, v119
	v_add3_u32 v2, s4, v2, v3
	v_mul_f32_e32 v3, 0xbfb8aa3b, v10
	v_exp_f32_e32 v6, v3
	v_mul_f32_e32 v3, 0xbfb8aa3b, v13
	v_exp_f32_e32 v7, v3
	ds_read_b128 v[2:5], v2
	v_add_f32_e32 v6, 1.0, v6
	v_rcp_f32_e32 v14, v6
	v_add_f32_e32 v6, 1.0, v7
	v_rcp_f32_e32 v15, v6
	v_mul_lo_u32 v6, v106, s45
	v_add3_u32 v0, s4, v6, v0
	ds_read_b128 v[6:9], v0
	s_waitcnt lgkmcnt(1)
	v_and_b32_e32 v11, 0xffff0000, v2
	v_lshlrev_b32_e32 v12, 16, v2
	v_pk_mul_f32 v[10:11], v[12:13], v[10:11]
	v_lshlrev_b32_e32 v12, 16, v71
	v_pk_mul_f32 v[10:11], v[14:15], v[10:11]
	v_and_b32_e32 v15, 0xffff0000, v71
	v_mul_f32_e32 v0, 0xbfb8aa3b, v12
	v_exp_f32_e32 v0, v0
	v_mul_f32_e32 v2, 0xbfb8aa3b, v15
	v_exp_f32_e32 v13, v2
	v_cvt_pk_bf16_f32 v2, v10, v11
	v_add_f32_e32 v0, 1.0, v0
	v_rcp_f32_e32 v10, v0
	v_add_f32_e32 v0, 1.0, v13
	v_rcp_f32_e32 v11, v0
	v_and_b32_e32 v13, 0xffff0000, v3
	v_lshlrev_b32_e32 v14, 16, v3
	v_pk_mul_f32 v[12:13], v[14:15], v[12:13]
	v_and_b32_e32 v15, 0xffff0000, v72
	v_pk_mul_f32 v[10:11], v[10:11], v[12:13]
	v_lshlrev_b32_e32 v12, 16, v72
	v_mul_f32_e32 v0, 0xbfb8aa3b, v12
	v_exp_f32_e32 v0, v0
	v_mul_f32_e32 v3, 0xbfb8aa3b, v15
	v_exp_f32_e32 v13, v3
	v_cvt_pk_bf16_f32 v3, v10, v11
	v_add_f32_e32 v0, 1.0, v0
	v_rcp_f32_e32 v10, v0
	v_add_f32_e32 v0, 1.0, v13
	v_rcp_f32_e32 v11, v0
	v_and_b32_e32 v13, 0xffff0000, v4
	v_lshlrev_b32_e32 v14, 16, v4
	v_pk_mul_f32 v[12:13], v[14:15], v[12:13]
	v_and_b32_e32 v15, 0xffff0000, v73
	v_pk_mul_f32 v[10:11], v[10:11], v[12:13]
	v_lshlrev_b32_e32 v12, 16, v73
	v_mul_f32_e32 v0, 0xbfb8aa3b, v12
	v_exp_f32_e32 v0, v0
	v_mul_f32_e32 v4, 0xbfb8aa3b, v15
	v_exp_f32_e32 v13, v4
	v_cvt_pk_bf16_f32 v4, v10, v11
	v_add_f32_e32 v0, 1.0, v0
	v_rcp_f32_e32 v10, v0
	v_add_f32_e32 v0, 1.0, v13
	v_rcp_f32_e32 v11, v0
	v_and_b32_e32 v13, 0xffff0000, v5
	v_lshlrev_b32_e32 v14, 16, v5
	v_pk_mul_f32 v[12:13], v[14:15], v[12:13]
	s_waitcnt vmcnt(6)
	v_and_b32_e32 v15, 0xffff0000, v66
	v_pk_mul_f32 v[10:11], v[10:11], v[12:13]
	v_lshlrev_b32_e32 v12, 16, v66
	v_mul_f32_e32 v0, 0xbfb8aa3b, v12
	v_exp_f32_e32 v0, v0
	v_mul_f32_e32 v13, 0xbfb8aa3b, v15
	v_exp_f32_e32 v13, v13
	v_cvt_pk_bf16_f32 v5, v10, v11
	v_lshlrev_b64 v[10:11], 12, v[102:103]
	v_lshl_add_u64 v[10:11], s[0:1], 0, v[10:11]
	v_lshl_add_u64 v[10:11], v[10:11], 0, v[104:105]
	v_add_f32_e32 v0, 1.0, v0
	global_store_dwordx4 v[10:11], v[2:5], off
	s_waitcnt lgkmcnt(0)
	v_lshlrev_b32_e32 v14, 16, v6
	v_and_b32_e32 v11, 0xffff0000, v67
	v_rcp_f32_e32 v2, v0
	v_add_f32_e32 v0, 1.0, v13
	v_rcp_f32_e32 v3, v0
	v_and_b32_e32 v13, 0xffff0000, v6
	v_pk_mul_f32 v[4:5], v[14:15], v[12:13]
	v_lshlrev_b32_e32 v10, 16, v7
	v_pk_mul_f32 v[2:3], v[2:3], v[4:5]
	v_lshlrev_b32_e32 v4, 16, v67
	v_mul_f32_e32 v0, 0xbfb8aa3b, v4
	v_exp_f32_e32 v0, v0
	v_mul_f32_e32 v5, 0xbfb8aa3b, v11
	v_exp_f32_e32 v5, v5
	v_lshlrev_b32_e32 v6, 16, v68
	v_add_f32_e32 v0, 1.0, v0
	v_rcp_f32_e32 v12, v0
	v_add_f32_e32 v0, 1.0, v5
	v_and_b32_e32 v5, 0xffff0000, v7
	v_rcp_f32_e32 v13, v0
	v_pk_mul_f32 v[4:5], v[10:11], v[4:5]
	v_and_b32_e32 v11, 0xffff0000, v68
	v_mul_f32_e32 v0, 0xbfb8aa3b, v6
	v_cvt_pk_bf16_f32 v2, v2, v3
	v_exp_f32_e32 v0, v0
	v_mul_f32_e32 v3, 0xbfb8aa3b, v11
	v_exp_f32_e32 v7, v3
	v_pk_mul_f32 v[4:5], v[12:13], v[4:5]
	v_add_f32_e32 v0, 1.0, v0
	v_cvt_pk_bf16_f32 v3, v4, v5
	v_rcp_f32_e32 v4, v0
	v_add_f32_e32 v0, 1.0, v7
	v_rcp_f32_e32 v5, v0
	v_and_b32_e32 v7, 0xffff0000, v8
	v_lshlrev_b32_e32 v10, 16, v8
	v_pk_mul_f32 v[6:7], v[10:11], v[6:7]
	v_and_b32_e32 v11, 0xffff0000, v69
	v_pk_mul_f32 v[4:5], v[4:5], v[6:7]
	v_lshlrev_b32_e32 v6, 16, v69
	v_mul_f32_e32 v0, 0xbfb8aa3b, v6
	v_exp_f32_e32 v0, v0
	v_mul_f32_e32 v7, 0xbfb8aa3b, v11
	v_exp_f32_e32 v7, v7
	v_lshlrev_b32_e32 v10, 16, v9
	v_add_f32_e32 v0, 1.0, v0
	v_rcp_f32_e32 v12, v0
	v_add_f32_e32 v0, 1.0, v7
	v_rcp_f32_e32 v13, v0
	v_and_b32_e32 v7, 0xffff0000, v9
	v_pk_mul_f32 v[6:7], v[10:11], v[6:7]
	v_cvt_pk_bf16_f32 v4, v4, v5
	v_pk_mul_f32 v[6:7], v[12:13], v[6:7]
	s_nop 0
	v_cvt_pk_bf16_f32 v5, v6, v7
	v_lshlrev_b64 v[6:7], 12, v[98:99]
	v_lshl_add_u64 v[6:7], s[0:1], 0, v[6:7]
	v_lshl_add_u64 v[6:7], v[6:7], 0, v[100:101]
	global_store_dwordx4 v[6:7], v[2:5], off
	s_barrier
	s_cbranch_scc0 .LBB0_662

.LBB0_646:
	v_mul_lo_u32 v157, v146, s45
	v_lshlrev_b32_e32 v158, 4, v0
	v_add3_u32 v0, 0, v157, v158
	s_waitcnt vmcnt(0)
	ds_write_b128 v0, v[14:17]
	v_mad_u64_u32 v[14:15], s[4:5], v146, 48, v[0:1]
	ds_write_b128 v14, v[10:13] offset:34816
	v_lshlrev_b64 v[10:11], 14, v[146:147]
	v_lshl_add_u64 v[10:11], s[20:21], 0, v[10:11]
	v_lshlrev_b64 v[12:13], 1, v[20:21]
	v_lshl_add_u64 v[10:11], v[10:11], 0, v[12:13]
	v_add_co_u32_e32 v10, vcc, s47, v10
	v_lshlrev_b64 v[14:15], 1, v[22:23]
	s_nop 0
	v_addc_co_u32_e32 v11, vcc, 0, v11, vcc
	global_load_dwordx4 v[130:133], v[10:11], off offset:-4096
	global_load_dwordx4 v[134:137], v[10:11], off
	v_lshlrev_b64 v[10:11], 14, v[148:149]
	v_lshl_add_u64 v[10:11], s[20:21], 0, v[10:11]
	v_lshl_add_u64 v[10:11], v[10:11], 0, v[14:15]
	v_add_co_u32_e32 v10, vcc, s47, v10
	v_mul_lo_u32 v160, v148, s45
	s_nop 0
	v_addc_co_u32_e32 v11, vcc, 0, v11, vcc
	global_load_dwordx4 v[138:141], v[10:11], off offset:-4096
	global_load_dwordx4 v[142:145], v[10:11], off
	v_lshlrev_b32_e32 v161, 4, v32
	v_add3_u32 v0, 0, v160, v161
	ds_write_b128 v0, v[2:5]
	v_mad_u64_u32 v[2:3], s[4:5], v148, 48, v[0:1]
	v_lshrrev_b32_e32 v0, 2, v18
	v_lshlrev_b32_e32 v163, 2, v31
	ds_write_b128 v2, v[6:9] offset:34816
	v_and_or_b32 v0, v0, 3, v163
	v_lshlrev_b32_e32 v2, 1, v18
	v_lshlrev_b32_e32 v3, 3, v18
	s_add_i32 s5, s33, s60
	v_lshl_add_u32 v149, v31, 4, 0
	v_mad_u32_u24 v0, v0, s46, 0
	v_and_b32_e32 v2, 32, v2
	v_and_b32_e32 v3, 24, v3
	v_lshl_add_u64 v[152:153], s[20:21], 0, v[14:15]
	v_mov_b32_e32 v14, v1
	v_mov_b32_e32 v15, v1
	v_mad_u32_u24 v162, v30, s45, v149
	v_add3_u32 v164, v0, v2, v3
	v_lshl_add_u64 v[150:151], s[20:21], 0, v[12:13]
	v_add_u32_e32 v195, s5, v30
	v_mov_b32_e32 v0, v1
	v_mov_b32_e32 v2, v1
	v_mov_b32_e32 v3, v1
	v_mov_b32_e32 v4, v1
	v_mov_b32_e32 v5, v1
	v_mov_b32_e32 v6, v1
	v_mov_b32_e32 v7, v1
	v_mov_b32_e32 v8, v1
	v_mov_b32_e32 v9, v1
	v_mov_b32_e32 v10, v1
	v_mov_b32_e32 v11, v1
	v_mov_b32_e32 v12, v1
	v_mov_b32_e32 v13, v1
	v_mov_b64_e32 v[64:65], v[14:15]
	v_mov_b64_e32 v[48:49], v[14:15]
	v_mov_b64_e32 v[32:33], v[14:15]
	s_lshl_b32 s6, s51, 2
	s_lshl_b32 s7, s51, 10
	v_mov_b64_e32 v[62:63], v[12:13]
	v_mov_b64_e32 v[60:61], v[10:11]
	v_mov_b64_e32 v[58:59], v[8:9]
	v_mov_b64_e32 v[56:57], v[6:7]
	v_mov_b64_e32 v[54:55], v[4:5]
	v_mov_b64_e32 v[52:53], v[2:3]
	v_mov_b64_e32 v[50:51], v[0:1]
	v_mov_b64_e32 v[46:47], v[12:13]
	v_mov_b64_e32 v[44:45], v[10:11]
	v_mov_b64_e32 v[42:43], v[8:9]
	v_mov_b64_e32 v[40:41], v[6:7]
	v_mov_b64_e32 v[38:39], v[4:5]
	v_mov_b64_e32 v[36:37], v[2:3]
	v_mov_b64_e32 v[34:35], v[0:1]
	v_mov_b64_e32 v[30:31], v[12:13]
	v_mov_b64_e32 v[28:29], v[10:11]
	v_mov_b64_e32 v[26:27], v[8:9]
	v_mov_b64_e32 v[24:25], v[6:7]
	v_mov_b64_e32 v[22:23], v[4:5]
	v_mov_b64_e32 v[20:21], v[2:3]
	v_mov_b64_e32 v[18:19], v[0:1]
	v_mov_b64_e32 v[16:17], v[14:15]
	s_mov_b32 s0, 2
	s_add_i32 s1, s6, 4
	v_mul_lo_u32 v159, v146, s46
	v_mul_lo_u32 v147, v148, s46
	s_mov_b32 s4, 0
	s_or_b32 s6, s6, 3
	v_or_b32_e32 v165, 32, v163
	v_or_b32_e32 v166, 33, v163
	v_or_b32_e32 v167, 2, v163
	v_or_b32_e32 v168, 34, v163
	v_or_b32_e32 v169, 3, v163
	v_or_b32_e32 v170, 35, v163
	v_or_b32_e32 v171, 8, v163
	v_or_b32_e32 v172, 40, v163
	v_or_b32_e32 v173, 9, v163
	v_or_b32_e32 v174, 41, v163
	v_or_b32_e32 v175, 10, v163
	v_or_b32_e32 v176, 42, v163
	v_or_b32_e32 v177, 11, v163
	v_or_b32_e32 v178, 43, v163
	v_or_b32_e32 v179, 16, v163
	v_or_b32_e32 v180, 48, v163
	v_or_b32_e32 v181, 17, v163
	v_or_b32_e32 v182, 49, v163
	v_or_b32_e32 v183, 18, v163
	v_or_b32_e32 v184, 50, v163
	v_or_b32_e32 v185, 19, v163
	v_or_b32_e32 v186, 51, v163
	v_or_b32_e32 v187, 24, v163
	v_or_b32_e32 v188, 56, v163
	v_or_b32_e32 v189, 25, v163
	v_or_b32_e32 v190, 57, v163
	v_or_b32_e32 v191, 26, v163
	v_or_b32_e32 v192, 58, v163
	v_or_b32_e32 v193, 27, v163
	v_or_b32_e32 v194, 59, v163
	s_addk_i32 s7, 0x400
	v_mov_b32_e32 v196, 0
	v_mov_b32_e32 v197, 0xf149f2ca
	s_mov_b32 s26, 63
	v_mov_b64_e32 v[14:15], v[12:13]
	v_mov_b64_e32 v[12:13], v[10:11]
	v_mov_b64_e32 v[10:11], v[8:9]
	v_mov_b64_e32 v[8:9], v[6:7]
	v_mov_b64_e32 v[6:7], v[4:5]
	v_mov_b64_e32 v[4:5], v[2:3]
	v_mov_b64_e32 v[2:3], v[0:1]
	s_waitcnt lgkmcnt(0)
	s_movk_i32 s68, 0x5000
	s_mov_b32 s69, 0
	s_mov_b32 s70, 0xe800
	s_mov_b32 s72, 0
	s_barrier
	v_readfirstlane_b32 s73, v255
	s_cmp_lt_u32 s73, 0x100
	s_cbranch_scc1 .Lyp649
	s_setprio 1
.Lyp649:
	s_branch .LBB0_649
.LBB0_649:
	s_add_i32 s27, s0, -2
	s_and_b32 s27, s27, 1
	s_xor_b32 s34, s27, 1
	s_mul_i32 s35, s34, 0x4400
	s_add_i32 s35, s35, 0
	s_mulk_i32 s34, 0xc00
	s_add_i32 s34, s35, s34
	v_add3_u32 v0, s35, v157, v158
	s_waitcnt vmcnt(3)
	ds_write_b128 v0, v[130:133]
	v_add3_u32 v0, s68, v159, v158
	s_waitcnt vmcnt(2)
	ds_write_b128 v0, v[134:137] offset:34816
	v_add3_u32 v0, s35, v160, v161
	s_cmp_lt_u32 s0, s1
	s_waitcnt vmcnt(1)
	ds_write_b128 v0, v[138:141]
	v_add3_u32 v0, s68, v147, v161
	s_cselect_b32 s34, s0, s6
	s_lshl_b32 s34, s34, 6
	v_add_u32_e32 v250, s34, v146
	v_ashrrev_i32_e32 v251, 31, v250
	v_lshlrev_b64 v[250:251], 14, v[250:251]
	v_lshl_add_u64 v[250:251], v[150:151], 0, v[250:251]
	v_add_co_u32_e32 v252, vcc, s42, v250
	s_waitcnt vmcnt(0)
	ds_write_b128 v0, v[142:145] offset:34816
	v_addc_co_u32_e32 v253, vcc, 0, v251, vcc
	v_add_co_u32_e32 v250, vcc, 0x2000, v250
	s_nop 1
	v_addc_co_u32_e32 v251, vcc, 0, v251, vcc
	global_load_dwordx4 v[130:133], v[252:253], off
	global_load_dwordx4 v[134:137], v[250:251], off
	v_add_u32_e32 v250, s34, v148
	v_ashrrev_i32_e32 v251, 31, v250
	v_lshlrev_b64 v[250:251], 14, v[250:251]
	v_lshl_add_u64 v[250:251], v[152:153], 0, v[250:251]
	v_add_co_u32_e32 v252, vcc, 0x1000, v250
	s_sub_i32 s34, s26, 63
	s_nop 0
	v_addc_co_u32_e32 v253, vcc, 0, v251, vcc
	v_add_co_u32_e32 v250, vcc, 0x2000, v250
	s_cmp_gt_i32 s34, s5
	s_nop 0
	v_addc_co_u32_e32 v251, vcc, 0, v251, vcc
	global_load_dwordx4 v[138:141], v[252:253], off
	global_load_dwordx4 v[142:145], v[250:251], off
	s_sub_i32 s34, s26, 63
	s_cmp_gt_i32 s34, s5
	s_cbranch_scc1 .Lff1a_inact
	s_cmp_eq_u32 s72, 0
	s_cbranch_scc1 .Lff1a_first
	s_mul_i32 s34, s27, 0x4400
	v_add_u32_e32 v0, s34, v162
	ds_read_b128 v[198:201], v0
	ds_read_b128 v[202:205], v0 offset:32
	ds_read_b128 v[206:209], v0 offset:8704
	ds_read_b128 v[210:213], v0 offset:8736
	v_add_u32_e32 v246, s4, v149
	v_add_u32_e32 v234, 0x12800, v246
	v_add_u32_e32 v235, 0x12880, v246
	v_add_u32_e32 v238, 0x12820, v246
	v_add_u32_e32 v239, 0x128a0, v246
	v_add_u32_e32 v242, 0x12840, v246
	v_add_u32_e32 v243, 0x128c0, v246
	v_add_u32_e32 v247, 0x12860, v246
	v_add_u32_e32 v246, 0x128e0, v246
	ds_read_b128 v[218:221], v234
	ds_read_b128 v[234:237], v235
	ds_read_b128 v[222:225], v238
	ds_read_b128 v[238:241], v239
	ds_read_b128 v[226:229], v242
	ds_read_b128 v[242:245], v243
	ds_read_b128 v[230:233], v247
	ds_read_b128 v[246:249], v246
	s_waitcnt lgkmcnt(1)
	v_mfma_f32_32x32x16_bf16 v[218:233], v[198:201], v[98:101], v[218:233]
	v_sub_f32_e32 v82, v82, v197
	v_sub_f32_e32 v83, v83, v197
	v_sub_f32_e32 v84, v84, v197
	v_sub_f32_e32 v85, v85, v197
	v_exp_f32_e32 v82, v82
	v_exp_f32_e32 v83, v83
	v_exp_f32_e32 v84, v84
	v_exp_f32_e32 v85, v85
	s_waitcnt lgkmcnt(0)
	v_mfma_f32_32x32x16_bf16 v[234:249], v[206:209], v[98:101], v[234:249]
	v_sub_f32_e32 v86, v86, v197
	v_sub_f32_e32 v87, v87, v197
	v_sub_f32_e32 v88, v88, v197
	v_sub_f32_e32 v89, v89, v197
	v_exp_f32_e32 v86, v86
	v_exp_f32_e32 v87, v87
	v_exp_f32_e32 v88, v88
	v_exp_f32_e32 v89, v89
	v_mfma_f32_32x32x16_bf16 v[218:233], v[202:205], v[102:105], v[218:233]
	v_sub_f32_e32 v66, v66, v197
	v_sub_f32_e32 v67, v67, v197
	v_sub_f32_e32 v68, v68, v197
	v_sub_f32_e32 v69, v69, v197
	v_exp_f32_e32 v66, v66
	v_exp_f32_e32 v67, v67
	v_exp_f32_e32 v68, v68
	v_exp_f32_e32 v69, v69
	ds_read_b128 v[198:201], v0 offset:64
	ds_read_b128 v[202:205], v0 offset:96
	ds_read_b128 v[206:209], v0 offset:8768
	ds_read_b128 v[214:217], v0 offset:8800
	v_mfma_f32_32x32x16_bf16 v[234:249], v[210:213], v[102:105], v[234:249]
	v_add_f32_e32 v250, v82, v86
	v_add_f32_e32 v251, v83, v87
	v_add_f32_e32 v252, v84, v88
	v_add_f32_e32 v253, v85, v89
	v_sub_f32_e32 v70, v70, v197
	v_sub_f32_e32 v71, v71, v197
	v_sub_f32_e32 v72, v72, v197
	v_sub_f32_e32 v73, v73, v197
	s_waitcnt lgkmcnt(3)
	v_mfma_f32_32x32x16_bf16 v[218:233], v[198:201], v[106:109], v[218:233]
	v_exp_f32_e32 v70, v70
	v_exp_f32_e32 v71, v71
	v_exp_f32_e32 v72, v72
	v_exp_f32_e32 v73, v73
	v_add_f32_e32 v250, v250, v66
	v_add_f32_e32 v251, v251, v67
	v_add_f32_e32 v252, v252, v68
	v_add_f32_e32 v253, v253, v69
	s_waitcnt lgkmcnt(1)
	v_mfma_f32_32x32x16_bf16 v[234:249], v[206:209], v[106:109], v[234:249]
	v_sub_f32_e32 v90, v90, v197
	v_sub_f32_e32 v91, v91, v197
	v_sub_f32_e32 v92, v92, v197
	v_sub_f32_e32 v93, v93, v197
	v_exp_f32_e32 v90, v90
	v_exp_f32_e32 v91, v91
	v_exp_f32_e32 v92, v92
	v_exp_f32_e32 v93, v93
	v_mfma_f32_32x32x16_bf16 v[218:233], v[202:205], v[110:113], v[218:233]
	v_add_f32_e32 v250, v250, v70
	v_add_f32_e32 v251, v251, v71
	v_add_f32_e32 v252, v252, v72
	v_add_f32_e32 v253, v253, v73
	v_sub_f32_e32 v94, v94, v197
	v_sub_f32_e32 v95, v95, v197
	v_sub_f32_e32 v96, v96, v197
	v_sub_f32_e32 v97, v97, v197
	ds_read_b128 v[198:201], v0 offset:128
	ds_read_b128 v[202:205], v0 offset:160
	ds_read_b128 v[206:209], v0 offset:8832
	ds_read_b128 v[210:213], v0 offset:8864
	s_waitcnt lgkmcnt(4)
	v_mfma_f32_32x32x16_bf16 v[234:249], v[214:217], v[110:113], v[234:249]
	v_exp_f32_e32 v94, v94
	v_exp_f32_e32 v95, v95
	v_exp_f32_e32 v96, v96
	v_exp_f32_e32 v97, v97
	v_add_f32_e32 v250, v250, v90
	v_add_f32_e32 v251, v251, v91
	v_add_f32_e32 v252, v252, v92
	v_add_f32_e32 v253, v253, v93
	s_waitcnt lgkmcnt(3)
	v_mfma_f32_32x32x16_bf16 v[218:233], v[198:201], v[114:117], v[218:233]
	v_sub_f32_e32 v74, v74, v197
	v_sub_f32_e32 v75, v75, v197
	v_sub_f32_e32 v76, v76, v197
	v_sub_f32_e32 v77, v77, v197
	v_exp_f32_e32 v74, v74
	v_exp_f32_e32 v75, v75
	v_exp_f32_e32 v76, v76
	v_exp_f32_e32 v77, v77
	s_waitcnt lgkmcnt(1)
	v_mfma_f32_32x32x16_bf16 v[234:249], v[206:209], v[114:117], v[234:249]
	v_add_f32_e32 v250, v250, v94
	v_add_f32_e32 v251, v251, v95
	v_add_f32_e32 v252, v252, v96
	v_add_f32_e32 v253, v253, v97
	v_sub_f32_e32 v78, v78, v197
	v_sub_f32_e32 v79, v79, v197
	v_sub_f32_e32 v80, v80, v197
	v_sub_f32_e32 v81, v81, v197
	v_mfma_f32_32x32x16_bf16 v[218:233], v[202:205], v[118:121], v[218:233]
	v_exp_f32_e32 v78, v78
	v_exp_f32_e32 v79, v79
	v_exp_f32_e32 v80, v80
	v_exp_f32_e32 v81, v81
	v_add_f32_e32 v250, v250, v74
	v_add_f32_e32 v251, v251, v75
	v_add_f32_e32 v252, v252, v76
	v_add_f32_e32 v253, v253, v77
	ds_read_b128 v[198:201], v0 offset:192
	ds_read_b128 v[202:205], v0 offset:224
	ds_read_b128 v[206:209], v0 offset:8896
	ds_read_b128 v[214:217], v0 offset:8928
	s_waitcnt lgkmcnt(4)
	v_mfma_f32_32x32x16_bf16 v[234:249], v[210:213], v[118:121], v[234:249]
	v_add_f32_e32 v250, v250, v78
	v_add_f32_e32 v251, v251, v79
	v_add_f32_e32 v252, v252, v80
	v_add_f32_e32 v253, v253, v81
	v_add_f32_e32 v250, v250, v251
	v_add_f32_e32 v252, v252, v253
	v_add_f32_e32 v250, v250, v252
	v_add_f32_e32 v196, v196, v250
	s_waitcnt lgkmcnt(3)
	v_mfma_f32_32x32x16_bf16 v[218:233], v[198:201], v[122:125], v[218:233]
	v_cvt_pk_bf16_f32 v73, v72, v73
	v_cvt_pk_bf16_f32 v72, v70, v71
	v_cvt_pk_bf16_f32 v71, v68, v69
	v_cvt_pk_bf16_f32 v70, v66, v67
	v_cvt_pk_bf16_f32 v66, v82, v83
	v_cvt_pk_bf16_f32 v67, v84, v85
	v_cvt_pk_bf16_f32 v68, v86, v87
	v_cvt_pk_bf16_f32 v69, v88, v89
	s_waitcnt lgkmcnt(1)
	v_mfma_f32_32x32x16_bf16 v[234:249], v[206:209], v[122:125], v[234:249]
	v_cvt_pk_bf16_f32 v81, v80, v81
	v_cvt_pk_bf16_f32 v80, v78, v79
	v_cvt_pk_bf16_f32 v79, v76, v77
	v_cvt_pk_bf16_f32 v78, v74, v75
	v_cvt_pk_bf16_f32 v74, v90, v91
	v_cvt_pk_bf16_f32 v75, v92, v93
	v_cvt_pk_bf16_f32 v76, v94, v95
	v_cvt_pk_bf16_f32 v77, v96, v97
	v_mfma_f32_32x32x16_bf16 v[218:233], v[202:205], v[126:129], v[218:233]
	s_waitcnt lgkmcnt(0)
	v_mfma_f32_32x32x16_bf16 v[234:249], v[214:217], v[126:129], v[234:249]
	s_cmp_le_i32 s26, s5
	s_cbranch_scc1 .Lff1a_z2
	v_cmp_le_i32_e32 vcc, v165, v195
	s_nop 8
	v_cndmask_b32_e32 v234, v155, v234, vcc
	v_cmp_lt_i32_e32 vcc, v163, v195
	s_nop 1
	v_cndmask_b32_e32 v219, v155, v219, vcc
	v_cmp_le_i32_e32 vcc, v163, v195
	s_nop 1
	v_cndmask_b32_e32 v218, v155, v218, vcc
	v_cmp_le_i32_e32 vcc, v166, v195
	s_nop 1
	v_cndmask_b32_e32 v235, v155, v235, vcc
	v_cmp_le_i32_e32 vcc, v167, v195
	s_nop 1
	v_cndmask_b32_e32 v220, v155, v220, vcc
	v_cmp_le_i32_e32 vcc, v168, v195
	s_nop 1
	v_cndmask_b32_e32 v236, v155, v236, vcc
	v_cmp_le_i32_e32 vcc, v169, v195
	s_nop 1
	v_cndmask_b32_e32 v221, v155, v221, vcc
	v_cmp_le_i32_e32 vcc, v170, v195
	s_nop 1
	v_cndmask_b32_e32 v237, v155, v237, vcc
	v_cmp_le_i32_e32 vcc, v171, v195
	s_nop 1
	v_cndmask_b32_e32 v222, v155, v222, vcc
	v_cmp_le_i32_e32 vcc, v172, v195
	s_nop 1
	v_cndmask_b32_e32 v238, v155, v238, vcc
	v_cmp_le_i32_e32 vcc, v173, v195
	s_nop 1
	v_cndmask_b32_e32 v223, v155, v223, vcc
	v_cmp_le_i32_e32 vcc, v174, v195
	s_nop 1
	v_cndmask_b32_e32 v239, v155, v239, vcc
	v_cmp_le_i32_e32 vcc, v175, v195
	s_nop 1
	v_cndmask_b32_e32 v224, v155, v224, vcc
	v_cmp_le_i32_e32 vcc, v176, v195
	s_nop 1
	v_cndmask_b32_e32 v240, v155, v240, vcc
	v_cmp_le_i32_e32 vcc, v177, v195
	s_nop 1
	v_cndmask_b32_e32 v225, v155, v225, vcc
	v_cmp_le_i32_e32 vcc, v178, v195
	s_nop 1
	v_cndmask_b32_e32 v241, v155, v241, vcc
	v_cmp_le_i32_e32 vcc, v179, v195
	s_nop 1
	v_cndmask_b32_e32 v226, v155, v226, vcc
	v_cmp_le_i32_e32 vcc, v180, v195
	s_nop 1
	v_cndmask_b32_e32 v242, v155, v242, vcc
	v_cmp_le_i32_e32 vcc, v181, v195
	s_nop 1
	v_cndmask_b32_e32 v227, v155, v227, vcc
	v_cmp_le_i32_e32 vcc, v182, v195
	s_nop 1
	v_cndmask_b32_e32 v243, v155, v243, vcc
	v_cmp_le_i32_e32 vcc, v183, v195
	s_nop 1
	v_cndmask_b32_e32 v228, v155, v228, vcc
	v_cmp_le_i32_e32 vcc, v184, v195
	s_nop 1
	v_cndmask_b32_e32 v244, v155, v244, vcc
	v_cmp_le_i32_e32 vcc, v185, v195
	s_nop 1
	v_cndmask_b32_e32 v229, v155, v229, vcc
	v_cmp_le_i32_e32 vcc, v186, v195
	s_nop 1
	v_cndmask_b32_e32 v245, v155, v245, vcc
	v_cmp_le_i32_e32 vcc, v187, v195
	s_nop 1
	v_cndmask_b32_e32 v230, v155, v230, vcc
	v_cmp_le_i32_e32 vcc, v188, v195
	s_nop 1
	v_cndmask_b32_e32 v246, v155, v246, vcc
	v_cmp_le_i32_e32 vcc, v189, v195
	s_nop 1
	v_cndmask_b32_e32 v231, v155, v231, vcc
	v_cmp_le_i32_e32 vcc, v190, v195
	s_nop 1
	v_cndmask_b32_e32 v247, v155, v247, vcc
	v_cmp_le_i32_e32 vcc, v191, v195
	s_nop 1
	v_cndmask_b32_e32 v232, v155, v232, vcc
	v_cmp_le_i32_e32 vcc, v192, v195
	s_nop 1
	v_cndmask_b32_e32 v248, v155, v248, vcc
	v_cmp_le_i32_e32 vcc, v193, v195
	s_nop 1
	v_cndmask_b32_e32 v233, v155, v233, vcc
	v_cmp_le_i32_e32 vcc, v194, v195
	s_nop 1
	v_cndmask_b32_e32 v249, v155, v249, vcc

.LBB0_654:
	s_setprio 0
	v_mov_b32_e32 v0, v196
	v_nop
	v_nop
	v_permlane32_swap_b32 v196, v0
	s_lshl_b32 s16, s16, 1
	v_add_f32_e32 v146, v196, v0
	v_ashrrev_i32_e32 v0, 31, v156
	v_lshrrev_b32_e32 v0, 28, v0
	v_add_u32_e32 v0, v156, v0
	s_waitcnt vmcnt(0)
	v_ashrrev_i32_e32 v144, 4, v0
	v_and_b32_e32 v0, -16, v0
	v_sub_u32_e32 v147, v156, v0
	v_lshlrev_b32_e32 v68, 3, v147
	v_ashrrev_i32_e32 v69, 31, v68
	v_add_u32_e32 v0, 64, v156
	v_lshlrev_b64 v[140:141], 1, v[68:69]
	v_ashrrev_i32_e32 v68, 31, v0
	v_lshrrev_b32_e32 v68, 28, v68
	v_ashrrev_i32_e32 v145, 31, v144
	v_add_u32_e32 v68, v0, v68
	v_lshl_add_u64 v[138:139], s[24:25], 0, v[144:145]
	v_ashrrev_i32_e32 v142, 4, v68
	v_lshlrev_b64 v[66:67], 14, v[138:139]
	v_and_b32_e32 v68, -16, v68
	v_ashrrev_i32_e32 v143, 31, v142
	v_lshl_add_u64 v[66:67], s[12:13], 0, v[66:67]
	v_sub_u32_e32 v145, v0, v68
	v_lshl_add_u64 v[132:133], s[24:25], 0, v[142:143]
	v_lshl_add_u64 v[66:67], v[66:67], 0, s[16:17]
	v_lshlrev_b64 v[68:69], 14, v[132:133]
	v_lshlrev_b32_e32 v70, 3, v145
	v_lshl_add_u64 v[66:67], v[66:67], 0, v[140:141]
	v_lshl_add_u64 v[68:69], s[12:13], 0, v[68:69]
	v_ashrrev_i32_e32 v71, 31, v70
	v_add_co_u32_e32 v66, vcc, s48, v66
	v_lshl_add_u64 v[68:69], v[68:69], 0, s[16:17]
	v_lshlrev_b64 v[134:135], 1, v[70:71]
	v_addc_co_u32_e32 v67, vcc, 0, v67, vcc
	v_lshl_add_u64 v[68:69], v[68:69], 0, v[134:135]
	v_add_co_u32_e32 v68, vcc, s48, v68
	v_add_u32_e32 v0, 0x80, v156
	s_nop 0
	v_addc_co_u32_e32 v69, vcc, 0, v69, vcc
	global_load_dwordx4 v[94:97], v[66:67], off
	global_load_dwordx4 v[90:93], v[68:69], off
	v_ashrrev_i32_e32 v66, 31, v0
	v_lshrrev_b32_e32 v66, 28, v66
	v_add_u32_e32 v66, v0, v66
	v_ashrrev_i32_e32 v136, 4, v66
	v_and_b32_e32 v66, -16, v66
	v_sub_u32_e32 v143, v0, v66
	v_lshlrev_b32_e32 v68, 3, v143
	v_ashrrev_i32_e32 v69, 31, v68
	v_add_u32_e32 v0, 0xc0, v156
	v_lshlrev_b64 v[128:129], 1, v[68:69]
	v_ashrrev_i32_e32 v68, 31, v0
	v_lshrrev_b32_e32 v68, 28, v68
	v_ashrrev_i32_e32 v137, 31, v136
	v_add_u32_e32 v68, v0, v68
	v_lshl_add_u64 v[126:127], s[24:25], 0, v[136:137]
	v_ashrrev_i32_e32 v130, 4, v68
	v_lshlrev_b64 v[66:67], 14, v[126:127]
	v_and_b32_e32 v68, -16, v68
	v_ashrrev_i32_e32 v131, 31, v130
	v_lshl_add_u64 v[66:67], s[12:13], 0, v[66:67]
	v_sub_u32_e32 v137, v0, v68
	v_lshl_add_u64 v[120:121], s[24:25], 0, v[130:131]
	v_lshl_add_u64 v[66:67], v[66:67], 0, s[16:17]
	v_lshlrev_b64 v[68:69], 14, v[120:121]
	v_lshlrev_b32_e32 v70, 3, v137
	v_lshl_add_u64 v[66:67], v[66:67], 0, v[128:129]
	v_lshl_add_u64 v[68:69], s[12:13], 0, v[68:69]
	v_ashrrev_i32_e32 v71, 31, v70
	v_add_co_u32_e32 v66, vcc, s48, v66
	v_lshl_add_u64 v[68:69], v[68:69], 0, s[16:17]
	v_lshlrev_b64 v[122:123], 1, v[70:71]
	v_addc_co_u32_e32 v67, vcc, 0, v67, vcc
	v_lshl_add_u64 v[68:69], v[68:69], 0, v[122:123]
	v_add_co_u32_e32 v68, vcc, s48, v68
	v_add_u32_e32 v0, 0x100, v156
	s_nop 0
	v_addc_co_u32_e32 v69, vcc, 0, v69, vcc
	global_load_dwordx4 v[86:89], v[66:67], off
	global_load_dwordx4 v[82:85], v[68:69], off
	v_ashrrev_i32_e32 v66, 31, v0
	v_lshrrev_b32_e32 v66, 28, v66
	v_add_u32_e32 v66, v0, v66
	v_ashrrev_i32_e32 v124, 4, v66
	v_and_b32_e32 v66, -16, v66
	v_sub_u32_e32 v131, v0, v66
	v_lshlrev_b32_e32 v68, 3, v131
	v_ashrrev_i32_e32 v69, 31, v68
	v_add_u32_e32 v0, 0x140, v156
	v_lshlrev_b64 v[116:117], 1, v[68:69]
	v_ashrrev_i32_e32 v68, 31, v0
	v_lshrrev_b32_e32 v68, 28, v68
	v_ashrrev_i32_e32 v125, 31, v124
	v_add_u32_e32 v68, v0, v68
	v_lshl_add_u64 v[114:115], s[24:25], 0, v[124:125]
	v_ashrrev_i32_e32 v118, 4, v68
	v_lshlrev_b64 v[66:67], 14, v[114:115]
	v_and_b32_e32 v68, -16, v68
	v_ashrrev_i32_e32 v119, 31, v118
	v_lshl_add_u64 v[66:67], s[12:13], 0, v[66:67]
	v_sub_u32_e32 v125, v0, v68
	v_lshl_add_u64 v[108:109], s[24:25], 0, v[118:119]
	v_lshl_add_u64 v[66:67], v[66:67], 0, s[16:17]
	v_lshlrev_b64 v[68:69], 14, v[108:109]
	v_lshlrev_b32_e32 v70, 3, v125
	v_lshl_add_u64 v[66:67], v[66:67], 0, v[116:117]
	v_lshl_add_u64 v[68:69], s[12:13], 0, v[68:69]
	v_ashrrev_i32_e32 v71, 31, v70
	v_add_co_u32_e32 v66, vcc, s48, v66
	v_lshl_add_u64 v[68:69], v[68:69], 0, s[16:17]
	v_lshlrev_b64 v[110:111], 1, v[70:71]
	v_addc_co_u32_e32 v67, vcc, 0, v67, vcc
	v_lshl_add_u64 v[68:69], v[68:69], 0, v[110:111]
	v_add_co_u32_e32 v68, vcc, s48, v68
	v_add_u32_e32 v0, 0x180, v156
	s_nop 0
	v_addc_co_u32_e32 v69, vcc, 0, v69, vcc
	global_load_dwordx4 v[78:81], v[66:67], off
	global_load_dwordx4 v[74:77], v[68:69], off
	v_ashrrev_i32_e32 v66, 31, v0
	v_lshrrev_b32_e32 v66, 28, v66
	v_add_u32_e32 v66, v0, v66
	v_ashrrev_i32_e32 v112, 4, v66
	v_and_b32_e32 v66, -16, v66
	v_sub_u32_e32 v119, v0, v66
	v_lshlrev_b32_e32 v68, 3, v119
	v_ashrrev_i32_e32 v69, 31, v68
	v_add_u32_e32 v0, 0x1c0, v156
	v_lshlrev_b64 v[104:105], 1, v[68:69]
	v_ashrrev_i32_e32 v68, 31, v0
	v_lshrrev_b32_e32 v68, 28, v68
	v_ashrrev_i32_e32 v113, 31, v112
	v_add_u32_e32 v68, v0, v68
	v_lshl_add_u64 v[102:103], s[24:25], 0, v[112:113]
	v_ashrrev_i32_e32 v106, 4, v68
	v_lshlrev_b64 v[66:67], 14, v[102:103]
	v_and_b32_e32 v68, -16, v68
	v_ashrrev_i32_e32 v107, 31, v106
	s_and_b32 s0, s49, 7
	v_lshl_add_u64 v[66:67], s[12:13], 0, v[66:67]
	v_sub_u32_e32 v0, v0, v68
	v_lshl_add_u64 v[98:99], s[24:25], 0, v[106:107]
	s_lshl_b32 s7, s0, 8
	s_lshl_b32 s6, s0, 10
	v_lshl_add_u64 v[66:67], v[66:67], 0, s[16:17]
	v_lshlrev_b64 v[68:69], 14, v[98:99]
	v_lshlrev_b32_e32 v70, 3, v0
	v_div_scale_f32 v107, s[0:1], v146, v146, 1.0
	v_lshl_add_u64 v[66:67], v[66:67], 0, v[104:105]
	v_lshl_add_u64 v[68:69], s[12:13], 0, v[68:69]
	v_ashrrev_i32_e32 v71, 31, v70
	v_rcp_f32_e32 v113, v107
	v_add_co_u32_e32 v66, vcc, s48, v66
	v_lshl_add_u64 v[68:69], v[68:69], 0, s[16:17]
	v_lshlrev_b64 v[100:101], 1, v[70:71]
	v_addc_co_u32_e32 v67, vcc, 0, v67, vcc
	v_lshl_add_u64 v[68:69], v[68:69], 0, v[100:101]
	v_add_co_u32_e32 v68, vcc, s48, v68
	v_fma_f32 v148, -v107, v113, 1.0
	s_nop 0
	v_addc_co_u32_e32 v69, vcc, 0, v69, vcc
	v_fmac_f32_e32 v113, v148, v113
	v_div_scale_f32 v148, vcc, 1.0, v146, 1.0
	v_mul_f32_e32 v149, v148, v113
	v_fma_f32 v150, -v107, v149, v148
	v_fmac_f32_e32 v149, v150, v113
	v_fma_f32 v107, -v107, v149, v148
	v_div_fmas_f32 v107, v107, v113, v149
	v_div_fixup_f32 v146, v107, v146, 1.0
	v_pk_mul_f32 v[50:51], v[50:51], v[146:147] op_sel_hi:[1,0]
	v_pk_mul_f32 v[52:53], v[52:53], v[146:147] op_sel_hi:[1,0]
	s_mulk_i32 s33, 0x110
	v_and_b32_e32 v107, 31, v156
	v_cvt_pk_bf16_f32 v50, v50, v51
	v_cvt_pk_bf16_f32 v51, v52, v53
	v_ashrrev_i32_e32 v52, 2, v156
	v_pk_mul_f32 v[2:3], v[2:3], v[146:147] op_sel_hi:[1,0]
	v_pk_mul_f32 v[4:5], v[4:5], v[146:147] op_sel_hi:[1,0]
	s_add_i32 s4, s33, 0
	v_mul_u32_u24_e32 v107, 0x110, v107
	v_and_b32_e32 v52, -8, v52
	v_cvt_pk_bf16_f32 v2, v2, v3
	v_cvt_pk_bf16_f32 v3, v4, v5
	v_pk_mul_f32 v[4:5], v[6:7], v[146:147] op_sel_hi:[1,0]
	v_pk_mul_f32 v[6:7], v[8:9], v[146:147] op_sel_hi:[1,0]
	v_add3_u32 v107, s4, v107, v52
	v_cvt_pk_bf16_f32 v4, v4, v5
	v_cvt_pk_bf16_f32 v5, v6, v7
	global_load_dwordx4 v[70:73], v[66:67], off
	s_nop 0
	global_load_dwordx4 v[66:69], v[68:69], off
	v_pk_mul_f32 v[34:35], v[34:35], v[146:147] op_sel_hi:[1,0]
	v_pk_mul_f32 v[36:37], v[36:37], v[146:147] op_sel_hi:[1,0]
	v_pk_mul_f32 v[18:19], v[18:19], v[146:147] op_sel_hi:[1,0]
	v_pk_mul_f32 v[20:21], v[20:21], v[146:147] op_sel_hi:[1,0]
	ds_write2_b64 v107, v[2:3], v[4:5] offset0:24 offset1:26
	v_pk_mul_f32 v[2:3], v[10:11], v[146:147] op_sel_hi:[1,0]
	v_pk_mul_f32 v[4:5], v[12:13], v[146:147] op_sel_hi:[1,0]
	v_pk_mul_f32 v[52:53], v[54:55], v[146:147] op_sel_hi:[1,0]
	v_pk_mul_f32 v[54:55], v[56:57], v[146:147] op_sel_hi:[1,0]
	v_cvt_pk_bf16_f32 v34, v34, v35
	v_cvt_pk_bf16_f32 v35, v36, v37
	v_pk_mul_f32 v[36:37], v[38:39], v[146:147] op_sel_hi:[1,0]
	v_pk_mul_f32 v[38:39], v[40:41], v[146:147] op_sel_hi:[1,0]
	v_cvt_pk_bf16_f32 v18, v18, v19
	v_cvt_pk_bf16_f32 v19, v20, v21
	v_pk_mul_f32 v[20:21], v[22:23], v[146:147] op_sel_hi:[1,0]
	v_pk_mul_f32 v[22:23], v[24:25], v[146:147] op_sel_hi:[1,0]
	v_cvt_pk_bf16_f32 v2, v2, v3
	v_cvt_pk_bf16_f32 v3, v4, v5
	v_pk_mul_f32 v[4:5], v[14:15], v[146:147] op_sel_hi:[1,0]
	v_pk_mul_f32 v[6:7], v[16:17], v[146:147] op_sel_hi:[1,0]
	v_cvt_pk_bf16_f32 v52, v52, v53
	v_cvt_pk_bf16_f32 v53, v54, v55
	v_cvt_pk_bf16_f32 v36, v36, v37
	v_cvt_pk_bf16_f32 v37, v38, v39
	v_cvt_pk_bf16_f32 v20, v20, v21
	v_cvt_pk_bf16_f32 v21, v22, v23
	v_cvt_pk_bf16_f32 v4, v4, v5
	v_cvt_pk_bf16_f32 v5, v6, v7
	ds_write2_b64 v107, v[50:51], v[52:53] offset1:2
	v_pk_mul_f32 v[50:51], v[58:59], v[146:147] op_sel_hi:[1,0]
	v_pk_mul_f32 v[52:53], v[60:61], v[146:147] op_sel_hi:[1,0]
	ds_write2_b64 v107, v[34:35], v[36:37] offset0:8 offset1:10
	v_pk_mul_f32 v[34:35], v[42:43], v[146:147] op_sel_hi:[1,0]
	v_pk_mul_f32 v[36:37], v[44:45], v[146:147] op_sel_hi:[1,0]
	ds_write2_b64 v107, v[18:19], v[20:21] offset0:16 offset1:18
	v_pk_mul_f32 v[18:19], v[26:27], v[146:147] op_sel_hi:[1,0]
	v_pk_mul_f32 v[20:21], v[28:29], v[146:147] op_sel_hi:[1,0]
	ds_write2_b64 v107, v[2:3], v[4:5] offset0:28 offset1:30
	v_mul_lo_u32 v2, v144, s45
	v_lshlrev_b32_e32 v3, 4, v147
	s_waitcnt vmcnt(7)
	v_lshlrev_b32_e32 v10, 16, v94
	v_cvt_pk_bf16_f32 v50, v50, v51
	v_cvt_pk_bf16_f32 v51, v52, v53
	v_pk_mul_f32 v[52:53], v[62:63], v[146:147] op_sel_hi:[1,0]
	v_pk_mul_f32 v[54:55], v[64:65], v[146:147] op_sel_hi:[1,0]
	v_cvt_pk_bf16_f32 v34, v34, v35
	v_cvt_pk_bf16_f32 v35, v36, v37
	v_pk_mul_f32 v[36:37], v[46:47], v[146:147] op_sel_hi:[1,0]
	v_pk_mul_f32 v[38:39], v[48:49], v[146:147] op_sel_hi:[1,0]
	v_cvt_pk_bf16_f32 v18, v18, v19
	v_cvt_pk_bf16_f32 v19, v20, v21
	v_pk_mul_f32 v[20:21], v[30:31], v[146:147] op_sel_hi:[1,0]
	v_pk_mul_f32 v[22:23], v[32:33], v[146:147] op_sel_hi:[1,0]
	v_add3_u32 v2, s4, v2, v3
	v_and_b32_e32 v13, 0xffff0000, v94
	v_mul_f32_e32 v3, 0xbfb8aa3b, v10
	v_cvt_pk_bf16_f32 v52, v52, v53
	v_cvt_pk_bf16_f32 v53, v54, v55
	v_cvt_pk_bf16_f32 v36, v36, v37
	v_cvt_pk_bf16_f32 v37, v38, v39
	v_cvt_pk_bf16_f32 v20, v20, v21
	v_cvt_pk_bf16_f32 v21, v22, v23
	v_exp_f32_e32 v6, v3
	v_mul_f32_e32 v3, 0xbfb8aa3b, v13
	ds_write2_b64 v107, v[50:51], v[52:53] offset0:4 offset1:6
	ds_write2_b64 v107, v[34:35], v[36:37] offset0:12 offset1:14
	ds_write2_b64 v107, v[18:19], v[20:21] offset0:20 offset1:22
	v_exp_f32_e32 v7, v3
	s_waitcnt lgkmcnt(0)
	ds_read_b128 v[2:5], v2
	v_add_f32_e32 v6, 1.0, v6
	v_rcp_f32_e32 v14, v6
	v_add_f32_e32 v6, 1.0, v7
	v_rcp_f32_e32 v15, v6
	v_mul_lo_u32 v6, v142, s45
	v_lshlrev_b32_e32 v7, 4, v145
	v_add3_u32 v6, s4, v6, v7
	ds_read_b128 v[6:9], v6
	s_waitcnt lgkmcnt(1)
	v_and_b32_e32 v11, 0xffff0000, v2
	v_lshlrev_b32_e32 v12, 16, v2
	v_pk_mul_f32 v[10:11], v[12:13], v[10:11]
	v_lshlrev_b32_e32 v12, 16, v95
	v_pk_mul_f32 v[10:11], v[14:15], v[10:11]
	v_and_b32_e32 v15, 0xffff0000, v95
	v_mul_f32_e32 v2, 0xbfb8aa3b, v12
	v_exp_f32_e32 v13, v2
	v_mul_f32_e32 v2, 0xbfb8aa3b, v15
	v_exp_f32_e32 v14, v2
	v_cvt_pk_bf16_f32 v2, v10, v11
	v_add_f32_e32 v10, 1.0, v13
	v_rcp_f32_e32 v10, v10
	v_add_f32_e32 v11, 1.0, v14
	v_rcp_f32_e32 v11, v11
	v_and_b32_e32 v13, 0xffff0000, v3
	v_lshlrev_b32_e32 v14, 16, v3
	v_pk_mul_f32 v[12:13], v[14:15], v[12:13]
	v_and_b32_e32 v15, 0xffff0000, v96
	v_pk_mul_f32 v[10:11], v[10:11], v[12:13]
	v_lshlrev_b32_e32 v12, 16, v96
	v_mul_f32_e32 v3, 0xbfb8aa3b, v12
	v_exp_f32_e32 v13, v3
	v_mul_f32_e32 v3, 0xbfb8aa3b, v15
	v_exp_f32_e32 v14, v3
	v_cvt_pk_bf16_f32 v3, v10, v11
	v_add_f32_e32 v10, 1.0, v13
	v_rcp_f32_e32 v10, v10
	v_add_f32_e32 v11, 1.0, v14
	v_rcp_f32_e32 v11, v11
	v_and_b32_e32 v13, 0xffff0000, v4
	v_lshlrev_b32_e32 v14, 16, v4
	v_pk_mul_f32 v[12:13], v[14:15], v[12:13]
	v_and_b32_e32 v15, 0xffff0000, v97
	v_pk_mul_f32 v[10:11], v[10:11], v[12:13]
	v_lshlrev_b32_e32 v12, 16, v97
	v_mul_f32_e32 v4, 0xbfb8aa3b, v12
	v_exp_f32_e32 v13, v4
	v_mul_f32_e32 v4, 0xbfb8aa3b, v15
	v_exp_f32_e32 v14, v4
	v_cvt_pk_bf16_f32 v4, v10, v11
	v_add_f32_e32 v10, 1.0, v13
	v_rcp_f32_e32 v10, v10
	v_add_f32_e32 v11, 1.0, v14
	v_rcp_f32_e32 v11, v11
	v_and_b32_e32 v13, 0xffff0000, v5
	v_lshlrev_b32_e32 v14, 16, v5
	v_pk_mul_f32 v[12:13], v[14:15], v[12:13]
	s_waitcnt vmcnt(6)
	v_and_b32_e32 v15, 0xffff0000, v90
	v_pk_mul_f32 v[10:11], v[10:11], v[12:13]
	v_lshlrev_b32_e32 v12, 16, v90
	s_addk_i32 s6, 0x400
	v_mul_f32_e32 v13, 0xbfb8aa3b, v12
	v_mul_f32_e32 v14, 0xbfb8aa3b, v15
	s_add_u32 s0, s36, s16
	v_exp_f32_e32 v13, v13
	v_exp_f32_e32 v14, v14
	s_addc_u32 s1, s37, 0
	v_cvt_pk_bf16_f32 v5, v10, v11
	v_lshlrev_b64 v[10:11], 12, v[138:139]
	v_lshl_add_u64 v[10:11], s[0:1], 0, v[10:11]
	v_lshl_add_u64 v[10:11], v[10:11], 0, v[140:141]
	global_store_dwordx4 v[10:11], v[2:5], off
	v_and_b32_e32 v11, 0xffff0000, v91
	s_waitcnt lgkmcnt(0)
	v_lshlrev_b32_e32 v10, 16, v7
	v_add_f32_e32 v2, 1.0, v13
	v_add_f32_e32 v3, 1.0, v14
	v_rcp_f32_e32 v2, v2
	v_rcp_f32_e32 v3, v3
	v_and_b32_e32 v13, 0xffff0000, v6
	v_lshlrev_b32_e32 v14, 16, v6
	v_pk_mul_f32 v[4:5], v[14:15], v[12:13]
	v_mul_f32_e32 v6, 0xbfb8aa3b, v11
	v_pk_mul_f32 v[2:3], v[2:3], v[4:5]
	v_lshlrev_b32_e32 v4, 16, v91
	v_mul_f32_e32 v5, 0xbfb8aa3b, v4
	v_exp_f32_e32 v5, v5
	v_exp_f32_e32 v6, v6
	v_cvt_pk_bf16_f32 v2, v2, v3
	v_lshlrev_b32_e32 v0, 4, v0
	v_add_f32_e32 v3, 1.0, v5
	v_rcp_f32_e32 v12, v3
	v_add_f32_e32 v3, 1.0, v6
	v_and_b32_e32 v5, 0xffff0000, v7
	v_lshlrev_b32_e32 v6, 16, v92
	v_rcp_f32_e32 v13, v3
	v_pk_mul_f32 v[4:5], v[10:11], v[4:5]
	v_and_b32_e32 v11, 0xffff0000, v92
	v_mul_f32_e32 v3, 0xbfb8aa3b, v6
	v_exp_f32_e32 v7, v3
	v_mul_f32_e32 v3, 0xbfb8aa3b, v11
	v_exp_f32_e32 v10, v3
	v_pk_mul_f32 v[4:5], v[12:13], v[4:5]
	v_mov_b32_e32 v28, v255
	v_cvt_pk_bf16_f32 v3, v4, v5
	v_add_f32_e32 v4, 1.0, v7
	v_add_f32_e32 v5, 1.0, v10
	v_rcp_f32_e32 v4, v4
	v_rcp_f32_e32 v5, v5
	v_and_b32_e32 v7, 0xffff0000, v8
	v_lshlrev_b32_e32 v10, 16, v8
	v_pk_mul_f32 v[6:7], v[10:11], v[6:7]
	v_and_b32_e32 v11, 0xffff0000, v93
	v_pk_mul_f32 v[4:5], v[4:5], v[6:7]
	v_lshlrev_b32_e32 v6, 16, v93
	v_mul_f32_e32 v7, 0xbfb8aa3b, v6
	v_exp_f32_e32 v7, v7
	v_mul_f32_e32 v8, 0xbfb8aa3b, v11
	v_exp_f32_e32 v8, v8
	v_cvt_pk_bf16_f32 v4, v4, v5
	v_add_f32_e32 v5, 1.0, v7
	v_rcp_f32_e32 v12, v5
	v_add_f32_e32 v5, 1.0, v8
	v_rcp_f32_e32 v13, v5
	v_and_b32_e32 v7, 0xffff0000, v9
	v_lshlrev_b32_e32 v10, 16, v9
	v_pk_mul_f32 v[6:7], v[10:11], v[6:7]
	s_waitcnt vmcnt(6)
	v_lshlrev_b32_e32 v10, 16, v86
	v_pk_mul_f32 v[6:7], v[12:13], v[6:7]
	v_and_b32_e32 v13, 0xffff0000, v86
	v_cvt_pk_bf16_f32 v5, v6, v7
	v_lshlrev_b64 v[6:7], 12, v[132:133]
	v_lshl_add_u64 v[6:7], s[0:1], 0, v[6:7]
	v_lshl_add_u64 v[6:7], v[6:7], 0, v[134:135]
	global_store_dwordx4 v[6:7], v[2:5], off
	s_lshl_b32 s27, s50, 8
	s_or_b32 s5, s22, s27
	v_mul_lo_u32 v2, v136, s45
	v_lshlrev_b32_e32 v3, 4, v143
	v_add3_u32 v2, s4, v2, v3
	v_mul_f32_e32 v3, 0xbfb8aa3b, v10
	v_exp_f32_e32 v6, v3
	v_mul_f32_e32 v3, 0xbfb8aa3b, v13
	v_exp_f32_e32 v7, v3
	ds_read_b128 v[2:5], v2
	v_add_f32_e32 v6, 1.0, v6
	v_rcp_f32_e32 v14, v6
	v_add_f32_e32 v6, 1.0, v7
	v_rcp_f32_e32 v15, v6
	v_mul_lo_u32 v6, v130, s45
	v_lshlrev_b32_e32 v7, 4, v137
	v_add3_u32 v6, s4, v6, v7
	ds_read_b128 v[6:9], v6
	s_waitcnt lgkmcnt(1)
	v_and_b32_e32 v11, 0xffff0000, v2
	v_lshlrev_b32_e32 v12, 16, v2
	v_pk_mul_f32 v[10:11], v[12:13], v[10:11]
	v_lshlrev_b32_e32 v12, 16, v87
	v_pk_mul_f32 v[10:11], v[14:15], v[10:11]
	v_and_b32_e32 v15, 0xffff0000, v87
	v_mul_f32_e32 v2, 0xbfb8aa3b, v12
	v_exp_f32_e32 v13, v2
	v_mul_f32_e32 v2, 0xbfb8aa3b, v15
	v_exp_f32_e32 v14, v2
	v_cvt_pk_bf16_f32 v2, v10, v11
	v_add_f32_e32 v10, 1.0, v13
	v_rcp_f32_e32 v10, v10
	v_add_f32_e32 v11, 1.0, v14
	v_rcp_f32_e32 v11, v11
	v_and_b32_e32 v13, 0xffff0000, v3
	v_lshlrev_b32_e32 v14, 16, v3
	v_pk_mul_f32 v[12:13], v[14:15], v[12:13]
	v_and_b32_e32 v15, 0xffff0000, v88
	v_pk_mul_f32 v[10:11], v[10:11], v[12:13]
	v_lshlrev_b32_e32 v12, 16, v88
	v_mul_f32_e32 v3, 0xbfb8aa3b, v12
	v_exp_f32_e32 v13, v3
	v_mul_f32_e32 v3, 0xbfb8aa3b, v15
	v_exp_f32_e32 v14, v3
	v_cvt_pk_bf16_f32 v3, v10, v11
	v_add_f32_e32 v10, 1.0, v13
	v_rcp_f32_e32 v10, v10
	v_add_f32_e32 v11, 1.0, v14
	v_rcp_f32_e32 v11, v11
	v_and_b32_e32 v13, 0xffff0000, v4
	v_lshlrev_b32_e32 v14, 16, v4
	v_pk_mul_f32 v[12:13], v[14:15], v[12:13]
	v_and_b32_e32 v15, 0xffff0000, v89
	v_pk_mul_f32 v[10:11], v[10:11], v[12:13]
	v_lshlrev_b32_e32 v12, 16, v89
	v_mul_f32_e32 v4, 0xbfb8aa3b, v12
	v_exp_f32_e32 v13, v4
	v_mul_f32_e32 v4, 0xbfb8aa3b, v15
	v_exp_f32_e32 v14, v4
	v_cvt_pk_bf16_f32 v4, v10, v11
	v_add_f32_e32 v10, 1.0, v13
	v_rcp_f32_e32 v10, v10
	v_add_f32_e32 v11, 1.0, v14
	v_rcp_f32_e32 v11, v11
	v_and_b32_e32 v13, 0xffff0000, v5
	v_lshlrev_b32_e32 v14, 16, v5
	v_pk_mul_f32 v[12:13], v[14:15], v[12:13]
	s_waitcnt vmcnt(6)
	v_and_b32_e32 v15, 0xffff0000, v82
	v_pk_mul_f32 v[10:11], v[10:11], v[12:13]
	v_lshlrev_b32_e32 v12, 16, v82
	v_mul_f32_e32 v13, 0xbfb8aa3b, v12
	v_mul_f32_e32 v14, 0xbfb8aa3b, v15
	v_exp_f32_e32 v13, v13
	v_exp_f32_e32 v14, v14
	v_cvt_pk_bf16_f32 v5, v10, v11
	v_lshlrev_b64 v[10:11], 12, v[126:127]
	v_lshl_add_u64 v[10:11], s[0:1], 0, v[10:11]
	v_lshl_add_u64 v[10:11], v[10:11], 0, v[128:129]
	global_store_dwordx4 v[10:11], v[2:5], off
	v_and_b32_e32 v11, 0xffff0000, v83
	s_waitcnt lgkmcnt(0)
	v_lshlrev_b32_e32 v10, 16, v7
	v_add_f32_e32 v2, 1.0, v13
	v_add_f32_e32 v3, 1.0, v14
	v_rcp_f32_e32 v2, v2
	v_rcp_f32_e32 v3, v3
	v_and_b32_e32 v13, 0xffff0000, v6
	v_lshlrev_b32_e32 v14, 16, v6
	v_pk_mul_f32 v[4:5], v[14:15], v[12:13]
	v_mul_f32_e32 v6, 0xbfb8aa3b, v11
	v_pk_mul_f32 v[2:3], v[2:3], v[4:5]
	v_lshlrev_b32_e32 v4, 16, v83
	v_mul_f32_e32 v5, 0xbfb8aa3b, v4
	v_exp_f32_e32 v5, v5
	v_exp_f32_e32 v6, v6
	v_cvt_pk_bf16_f32 v2, v2, v3
	s_lshl_b32 s33, s50, 2
	v_add_f32_e32 v3, 1.0, v5
	v_rcp_f32_e32 v12, v3
	v_add_f32_e32 v3, 1.0, v6
	v_and_b32_e32 v5, 0xffff0000, v7
	v_lshlrev_b32_e32 v6, 16, v84
	v_rcp_f32_e32 v13, v3
	v_pk_mul_f32 v[4:5], v[10:11], v[4:5]
	v_and_b32_e32 v11, 0xffff0000, v84
	v_mul_f32_e32 v3, 0xbfb8aa3b, v6
	v_exp_f32_e32 v7, v3
	v_mul_f32_e32 v3, 0xbfb8aa3b, v11
	v_exp_f32_e32 v10, v3
	v_pk_mul_f32 v[4:5], v[12:13], v[4:5]
	s_mov_b32 s24, 0
	v_cvt_pk_bf16_f32 v3, v4, v5
	v_add_f32_e32 v4, 1.0, v7
	v_add_f32_e32 v5, 1.0, v10
	v_rcp_f32_e32 v4, v4
	v_rcp_f32_e32 v5, v5
	v_and_b32_e32 v7, 0xffff0000, v8
	v_lshlrev_b32_e32 v10, 16, v8
	v_pk_mul_f32 v[6:7], v[10:11], v[6:7]
	v_and_b32_e32 v11, 0xffff0000, v85
	v_pk_mul_f32 v[4:5], v[4:5], v[6:7]
	v_lshlrev_b32_e32 v6, 16, v85
	v_mul_f32_e32 v7, 0xbfb8aa3b, v6
	v_exp_f32_e32 v7, v7
	v_mul_f32_e32 v8, 0xbfb8aa3b, v11
	v_exp_f32_e32 v8, v8
	v_cvt_pk_bf16_f32 v4, v4, v5
	v_add_f32_e32 v5, 1.0, v7
	v_rcp_f32_e32 v12, v5
	v_add_f32_e32 v5, 1.0, v8
	v_rcp_f32_e32 v13, v5
	v_and_b32_e32 v7, 0xffff0000, v9
	v_lshlrev_b32_e32 v10, 16, v9
	v_pk_mul_f32 v[6:7], v[10:11], v[6:7]
	s_waitcnt vmcnt(6)
	v_lshlrev_b32_e32 v10, 16, v78
	v_pk_mul_f32 v[6:7], v[12:13], v[6:7]
	v_and_b32_e32 v13, 0xffff0000, v78
	v_cvt_pk_bf16_f32 v5, v6, v7
	v_lshlrev_b64 v[6:7], 12, v[120:121]
	v_lshl_add_u64 v[6:7], s[0:1], 0, v[6:7]
	v_lshl_add_u64 v[6:7], v[6:7], 0, v[122:123]
	global_store_dwordx4 v[6:7], v[2:5], off
	s_mov_b32 s25, 2
	s_mov_b32 s26, 63
	v_mul_lo_u32 v2, v124, s45
	v_lshlrev_b32_e32 v3, 4, v131
	v_add3_u32 v2, s4, v2, v3
	v_mul_f32_e32 v3, 0xbfb8aa3b, v10
	v_exp_f32_e32 v6, v3
	v_mul_f32_e32 v3, 0xbfb8aa3b, v13
	v_exp_f32_e32 v7, v3
	ds_read_b128 v[2:5], v2
	v_add_f32_e32 v6, 1.0, v6
	v_rcp_f32_e32 v14, v6
	v_add_f32_e32 v6, 1.0, v7
	v_rcp_f32_e32 v15, v6
	v_mul_lo_u32 v6, v118, s45
	v_lshlrev_b32_e32 v7, 4, v125
	v_add3_u32 v6, s4, v6, v7
	ds_read_b128 v[6:9], v6
	s_waitcnt lgkmcnt(1)
	v_and_b32_e32 v11, 0xffff0000, v2
	v_lshlrev_b32_e32 v12, 16, v2
	v_pk_mul_f32 v[10:11], v[12:13], v[10:11]
	v_lshlrev_b32_e32 v12, 16, v79
	v_pk_mul_f32 v[10:11], v[14:15], v[10:11]
	v_and_b32_e32 v15, 0xffff0000, v79
	v_mul_f32_e32 v2, 0xbfb8aa3b, v12
	v_exp_f32_e32 v13, v2
	v_mul_f32_e32 v2, 0xbfb8aa3b, v15
	v_exp_f32_e32 v14, v2
	v_cvt_pk_bf16_f32 v2, v10, v11
	v_add_f32_e32 v10, 1.0, v13
	v_rcp_f32_e32 v10, v10
	v_add_f32_e32 v11, 1.0, v14
	v_rcp_f32_e32 v11, v11
	v_and_b32_e32 v13, 0xffff0000, v3
	v_lshlrev_b32_e32 v14, 16, v3
	v_pk_mul_f32 v[12:13], v[14:15], v[12:13]
	v_and_b32_e32 v15, 0xffff0000, v80
	v_pk_mul_f32 v[10:11], v[10:11], v[12:13]
	v_lshlrev_b32_e32 v12, 16, v80
	v_mul_f32_e32 v3, 0xbfb8aa3b, v12
	v_exp_f32_e32 v13, v3
	v_mul_f32_e32 v3, 0xbfb8aa3b, v15
	v_exp_f32_e32 v14, v3
	v_cvt_pk_bf16_f32 v3, v10, v11
	v_add_f32_e32 v10, 1.0, v13
	v_rcp_f32_e32 v10, v10
	v_add_f32_e32 v11, 1.0, v14
	v_rcp_f32_e32 v11, v11
	v_and_b32_e32 v13, 0xffff0000, v4
	v_lshlrev_b32_e32 v14, 16, v4
	v_pk_mul_f32 v[12:13], v[14:15], v[12:13]
	v_and_b32_e32 v15, 0xffff0000, v81
	v_pk_mul_f32 v[10:11], v[10:11], v[12:13]
	v_lshlrev_b32_e32 v12, 16, v81
	v_mul_f32_e32 v4, 0xbfb8aa3b, v12
	v_exp_f32_e32 v13, v4
	v_mul_f32_e32 v4, 0xbfb8aa3b, v15
	v_exp_f32_e32 v14, v4
	v_cvt_pk_bf16_f32 v4, v10, v11
	v_add_f32_e32 v10, 1.0, v13
	v_rcp_f32_e32 v10, v10
	v_add_f32_e32 v11, 1.0, v14
	v_rcp_f32_e32 v11, v11
	v_and_b32_e32 v13, 0xffff0000, v5
	v_lshlrev_b32_e32 v14, 16, v5
	v_pk_mul_f32 v[12:13], v[14:15], v[12:13]
	s_waitcnt vmcnt(6)
	v_and_b32_e32 v15, 0xffff0000, v74
	v_pk_mul_f32 v[10:11], v[10:11], v[12:13]
	v_lshlrev_b32_e32 v12, 16, v74
	v_mul_f32_e32 v13, 0xbfb8aa3b, v12
	v_mul_f32_e32 v14, 0xbfb8aa3b, v15
	v_exp_f32_e32 v13, v13
	v_exp_f32_e32 v14, v14
	v_cvt_pk_bf16_f32 v5, v10, v11
	v_lshlrev_b64 v[10:11], 12, v[114:115]
	v_lshl_add_u64 v[10:11], s[0:1], 0, v[10:11]
	v_lshl_add_u64 v[10:11], v[10:11], 0, v[116:117]
	global_store_dwordx4 v[10:11], v[2:5], off
	v_and_b32_e32 v11, 0xffff0000, v75
	s_waitcnt lgkmcnt(0)
	v_lshlrev_b32_e32 v10, 16, v7
	v_add_f32_e32 v2, 1.0, v13
	v_add_f32_e32 v3, 1.0, v14
	v_rcp_f32_e32 v2, v2
	v_rcp_f32_e32 v3, v3
	v_and_b32_e32 v13, 0xffff0000, v6
	v_lshlrev_b32_e32 v14, 16, v6
	v_pk_mul_f32 v[4:5], v[14:15], v[12:13]
	v_mul_f32_e32 v6, 0xbfb8aa3b, v11
	v_pk_mul_f32 v[2:3], v[2:3], v[4:5]
	v_lshlrev_b32_e32 v4, 16, v75
	v_mul_f32_e32 v5, 0xbfb8aa3b, v4
	v_exp_f32_e32 v5, v5
	v_exp_f32_e32 v6, v6
	v_cvt_pk_bf16_f32 v2, v2, v3
	v_mov_b32_e32 v196, 0
	v_add_f32_e32 v3, 1.0, v5
	v_rcp_f32_e32 v12, v3
	v_add_f32_e32 v3, 1.0, v6
	v_and_b32_e32 v5, 0xffff0000, v7
	v_lshlrev_b32_e32 v6, 16, v76
	v_rcp_f32_e32 v13, v3
	v_pk_mul_f32 v[4:5], v[10:11], v[4:5]
	v_and_b32_e32 v11, 0xffff0000, v76
	v_mul_f32_e32 v3, 0xbfb8aa3b, v6
	v_exp_f32_e32 v7, v3
	v_mul_f32_e32 v3, 0xbfb8aa3b, v11
	v_exp_f32_e32 v10, v3
	v_pk_mul_f32 v[4:5], v[12:13], v[4:5]
	v_mov_b32_e32 v197, 0xf149f2ca
	v_cvt_pk_bf16_f32 v3, v4, v5
	v_add_f32_e32 v4, 1.0, v7
	v_add_f32_e32 v5, 1.0, v10
	v_rcp_f32_e32 v4, v4
	v_rcp_f32_e32 v5, v5
	v_and_b32_e32 v7, 0xffff0000, v8
	v_lshlrev_b32_e32 v10, 16, v8
	v_pk_mul_f32 v[6:7], v[10:11], v[6:7]
	v_and_b32_e32 v11, 0xffff0000, v77
	v_pk_mul_f32 v[4:5], v[4:5], v[6:7]
	v_lshlrev_b32_e32 v6, 16, v77
	v_mul_f32_e32 v7, 0xbfb8aa3b, v6
	v_exp_f32_e32 v7, v7
	v_mul_f32_e32 v8, 0xbfb8aa3b, v11
	v_exp_f32_e32 v8, v8
	v_cvt_pk_bf16_f32 v4, v4, v5
	v_add_f32_e32 v5, 1.0, v7
	v_rcp_f32_e32 v12, v5
	v_add_f32_e32 v5, 1.0, v8
	v_rcp_f32_e32 v13, v5
	v_and_b32_e32 v7, 0xffff0000, v9
	v_lshlrev_b32_e32 v10, 16, v9
	v_pk_mul_f32 v[6:7], v[10:11], v[6:7]
	s_waitcnt vmcnt(6)
	v_lshlrev_b32_e32 v10, 16, v70
	v_pk_mul_f32 v[6:7], v[12:13], v[6:7]
	v_and_b32_e32 v13, 0xffff0000, v70
	v_cvt_pk_bf16_f32 v5, v6, v7
	v_lshlrev_b64 v[6:7], 12, v[108:109]
	v_lshl_add_u64 v[6:7], s[0:1], 0, v[6:7]
	v_lshl_add_u64 v[6:7], v[6:7], 0, v[110:111]
	global_store_dwordx4 v[6:7], v[2:5], off
	s_nop 1
	v_mul_lo_u32 v2, v112, s45
	v_lshlrev_b32_e32 v3, 4, v119
	v_add3_u32 v2, s4, v2, v3
	v_mul_f32_e32 v3, 0xbfb8aa3b, v10
	v_exp_f32_e32 v6, v3
	v_mul_f32_e32 v3, 0xbfb8aa3b, v13
	v_exp_f32_e32 v7, v3
	ds_read_b128 v[2:5], v2
	v_add_f32_e32 v6, 1.0, v6
	v_rcp_f32_e32 v14, v6
	v_add_f32_e32 v6, 1.0, v7
	v_rcp_f32_e32 v15, v6
	v_mul_lo_u32 v6, v106, s45
	v_add3_u32 v0, s4, v6, v0
	ds_read_b128 v[6:9], v0
	s_waitcnt lgkmcnt(1)
	v_and_b32_e32 v11, 0xffff0000, v2
	v_lshlrev_b32_e32 v12, 16, v2
	v_pk_mul_f32 v[10:11], v[12:13], v[10:11]
	v_lshlrev_b32_e32 v12, 16, v71
	v_pk_mul_f32 v[10:11], v[14:15], v[10:11]
	v_and_b32_e32 v15, 0xffff0000, v71
	v_mul_f32_e32 v0, 0xbfb8aa3b, v12
	v_exp_f32_e32 v0, v0
	v_mul_f32_e32 v2, 0xbfb8aa3b, v15
	v_exp_f32_e32 v13, v2
	v_cvt_pk_bf16_f32 v2, v10, v11
	v_add_f32_e32 v0, 1.0, v0
	v_rcp_f32_e32 v10, v0
	v_add_f32_e32 v0, 1.0, v13
	v_rcp_f32_e32 v11, v0
	v_and_b32_e32 v13, 0xffff0000, v3
	v_lshlrev_b32_e32 v14, 16, v3
	v_pk_mul_f32 v[12:13], v[14:15], v[12:13]
	v_and_b32_e32 v15, 0xffff0000, v72
	v_pk_mul_f32 v[10:11], v[10:11], v[12:13]
	v_lshlrev_b32_e32 v12, 16, v72
	v_mul_f32_e32 v0, 0xbfb8aa3b, v12
	v_exp_f32_e32 v0, v0
	v_mul_f32_e32 v3, 0xbfb8aa3b, v15
	v_exp_f32_e32 v13, v3
	v_cvt_pk_bf16_f32 v3, v10, v11
	v_add_f32_e32 v0, 1.0, v0
	v_rcp_f32_e32 v10, v0
	v_add_f32_e32 v0, 1.0, v13
	v_rcp_f32_e32 v11, v0
	v_and_b32_e32 v13, 0xffff0000, v4
	v_lshlrev_b32_e32 v14, 16, v4
	v_pk_mul_f32 v[12:13], v[14:15], v[12:13]
	v_and_b32_e32 v15, 0xffff0000, v73
	v_pk_mul_f32 v[10:11], v[10:11], v[12:13]
	v_lshlrev_b32_e32 v12, 16, v73
	v_mul_f32_e32 v0, 0xbfb8aa3b, v12
	v_exp_f32_e32 v0, v0
	v_mul_f32_e32 v4, 0xbfb8aa3b, v15
	v_exp_f32_e32 v13, v4
	v_cvt_pk_bf16_f32 v4, v10, v11
	v_add_f32_e32 v0, 1.0, v0
	v_rcp_f32_e32 v10, v0
	v_add_f32_e32 v0, 1.0, v13
	v_rcp_f32_e32 v11, v0
	v_and_b32_e32 v13, 0xffff0000, v5
	v_lshlrev_b32_e32 v14, 16, v5
	v_pk_mul_f32 v[12:13], v[14:15], v[12:13]
	s_waitcnt vmcnt(6)
	v_and_b32_e32 v15, 0xffff0000, v66
	v_pk_mul_f32 v[10:11], v[10:11], v[12:13]
	v_lshlrev_b32_e32 v12, 16, v66
	v_mul_f32_e32 v0, 0xbfb8aa3b, v12
	v_exp_f32_e32 v0, v0
	v_mul_f32_e32 v13, 0xbfb8aa3b, v15
	v_exp_f32_e32 v13, v13
	v_cvt_pk_bf16_f32 v5, v10, v11
	v_lshlrev_b64 v[10:11], 12, v[102:103]
	v_lshl_add_u64 v[10:11], s[0:1], 0, v[10:11]
	v_lshl_add_u64 v[10:11], v[10:11], 0, v[104:105]
	v_add_f32_e32 v0, 1.0, v0
	global_store_dwordx4 v[10:11], v[2:5], off
	s_waitcnt lgkmcnt(0)
	v_lshlrev_b32_e32 v14, 16, v6
	v_and_b32_e32 v11, 0xffff0000, v67
	v_rcp_f32_e32 v2, v0
	v_add_f32_e32 v0, 1.0, v13
	v_rcp_f32_e32 v3, v0
	v_and_b32_e32 v13, 0xffff0000, v6
	v_pk_mul_f32 v[4:5], v[14:15], v[12:13]
	v_lshlrev_b32_e32 v10, 16, v7
	v_pk_mul_f32 v[2:3], v[2:3], v[4:5]
	v_lshlrev_b32_e32 v4, 16, v67
	v_mul_f32_e32 v0, 0xbfb8aa3b, v4
	v_exp_f32_e32 v0, v0
	v_mul_f32_e32 v5, 0xbfb8aa3b, v11
	v_exp_f32_e32 v5, v5
	v_lshlrev_b32_e32 v6, 16, v68
	v_add_f32_e32 v0, 1.0, v0
	v_rcp_f32_e32 v12, v0
	v_add_f32_e32 v0, 1.0, v5
	v_and_b32_e32 v5, 0xffff0000, v7
	v_rcp_f32_e32 v13, v0
	v_pk_mul_f32 v[4:5], v[10:11], v[4:5]
	v_and_b32_e32 v11, 0xffff0000, v68
	v_mul_f32_e32 v0, 0xbfb8aa3b, v6
	v_cvt_pk_bf16_f32 v2, v2, v3
	v_exp_f32_e32 v0, v0
	v_mul_f32_e32 v3, 0xbfb8aa3b, v11
	v_exp_f32_e32 v7, v3
	v_pk_mul_f32 v[4:5], v[12:13], v[4:5]
	v_add_f32_e32 v0, 1.0, v0
	v_cvt_pk_bf16_f32 v3, v4, v5
	v_rcp_f32_e32 v4, v0
	v_add_f32_e32 v0, 1.0, v7
	v_rcp_f32_e32 v5, v0
	v_and_b32_e32 v7, 0xffff0000, v8
	v_lshlrev_b32_e32 v10, 16, v8
	v_pk_mul_f32 v[6:7], v[10:11], v[6:7]
	v_and_b32_e32 v11, 0xffff0000, v69
	v_pk_mul_f32 v[4:5], v[4:5], v[6:7]
	v_lshlrev_b32_e32 v6, 16, v69
	v_mul_f32_e32 v0, 0xbfb8aa3b, v6
	v_exp_f32_e32 v0, v0
	v_mul_f32_e32 v7, 0xbfb8aa3b, v11
	v_exp_f32_e32 v7, v7
	v_lshlrev_b32_e32 v10, 16, v9
	v_add_f32_e32 v0, 1.0, v0
	v_rcp_f32_e32 v12, v0
	v_add_f32_e32 v0, 1.0, v7
	v_rcp_f32_e32 v13, v0
	v_and_b32_e32 v7, 0xffff0000, v9
	v_pk_mul_f32 v[6:7], v[10:11], v[6:7]
	v_cvt_pk_bf16_f32 v4, v4, v5
	v_pk_mul_f32 v[6:7], v[12:13], v[6:7]
	s_nop 0
	v_cvt_pk_bf16_f32 v5, v6, v7
	v_lshlrev_b64 v[6:7], 12, v[98:99]
	v_lshl_add_u64 v[6:7], s[0:1], 0, v[6:7]
	v_lshl_add_u64 v[6:7], v[6:7], 0, v[100:101]
	global_store_dwordx4 v[6:7], v[2:5], off
	s_barrier
	s_nop 0
	v_ashrrev_i32_e32 v0, 31, v28
	v_lshrrev_b32_e32 v0, 28, v0
	v_add_u32_e32 v0, v28, v0
	v_ashrrev_i32_e32 v146, 4, v0
	v_and_b32_e32 v0, -16, v0
	v_sub_u32_e32 v29, v28, v0
	v_ashrrev_i32_e32 v147, 31, v146
	v_lshlrev_b32_e32 v4, 3, v29
	v_lshlrev_b64 v[2:3], 14, v[146:147]
	v_ashrrev_i32_e32 v5, 31, v4
	v_lshl_add_u64 v[2:3], s[20:21], 0, v[2:3]
	v_lshlrev_b64 v[18:19], 1, v[4:5]
	v_lshl_add_u64 v[20:21], v[2:3], 0, v[18:19]
	v_add_co_u32_e32 v6, vcc, s43, v20
	v_add_u32_e32 v0, 0x200, v28
	s_nop 0
	v_addc_co_u32_e32 v7, vcc, 0, v21, vcc
	global_load_dwordx4 v[2:5], v[6:7], off offset:-4096
	s_nop 0
	global_load_dwordx4 v[6:9], v[6:7], off
	v_ashrrev_i32_e32 v10, 31, v0
	v_readfirstlane_b32 s4, v28
	v_lshrrev_b32_e32 v10, 28, v10
	s_ashr_i32 s22, s4, 1
	v_add_u32_e32 v10, v0, v10
	s_andn2_b32 s22, s22, 31
	v_ashrrev_i32_e32 v148, 4, v10
	v_and_b32_e32 v10, -16, v10
	s_ashr_i32 s34, s22, 31
	v_sub_u32_e32 v30, v0, v10
	s_add_u32 s4, s5, s22
	v_ashrrev_i32_e32 v149, 31, v148
	v_lshlrev_b32_e32 v12, 3, v30
	v_and_b32_e32 v31, 31, v28
	s_addc_u32 s5, s23, s34
	v_lshlrev_b64 v[10:11], 14, v[148:149]
	v_ashrrev_i32_e32 v13, 31, v12
	v_or_b32_e32 v26, s4, v31
	v_mov_b32_e32 v27, s5
	v_lshl_add_u64 v[10:11], s[20:21], 0, v[10:11]
	v_lshlrev_b64 v[22:23], 1, v[12:13]
	v_lshlrev_b64 v[26:27], 14, v[26:27]
	v_lshl_add_u64 v[24:25], v[10:11], 0, v[22:23]
	v_bfe_u32 v32, v28, 5, 1
	v_lshl_add_u64 v[26:27], s[12:13], 0, v[26:27]
	v_add_co_u32_e32 v14, vcc, s43, v24
	v_lshl_add_u64 v[26:27], v[26:27], 0, s[16:17]
	v_lshlrev_b32_e32 v0, 4, v32
	v_addc_co_u32_e32 v15, vcc, 0, v25, vcc
	v_lshl_add_u64 v[26:27], v[26:27], 0, v[0:1]
	v_mul_lo_u32 v149, v146, s45
	v_lshlrev_b32_e32 v156, 4, v29
	global_load_dwordx4 v[10:13], v[14:15], off offset:-4096
	s_nop 0
	global_load_dwordx4 v[14:17], v[14:15], off
	s_nop 0
	global_load_dwordx4 v[98:101], v[26:27], off
	global_load_dwordx4 v[102:105], v[26:27], off offset:32
	global_load_dwordx4 v[106:109], v[26:27], off offset:64
	global_load_dwordx4 v[110:113], v[26:27], off offset:96
	global_load_dwordx4 v[114:117], v[26:27], off offset:128
	global_load_dwordx4 v[118:121], v[26:27], off offset:160
	global_load_dwordx4 v[122:125], v[26:27], off offset:192
	global_load_dwordx4 v[126:129], v[26:27], off offset:224
	v_add3_u32 v26, 0, v149, v156
	s_waitcnt vmcnt(0)
	v_mul_lo_u32 v158, v148, s45
	v_lshlrev_b32_e32 v159, 4, v30
	v_lshlrev_b32_e32 v163, 2, v32
	v_add_u32_e32 v161, 0, v0
	s_add_i32 s7, s7, s22
	v_and_b32_e32 v147, 63, v28
	v_mad_u32_u24 v162, v31, s45, v161
	v_lshl_add_u64 v[150:151], s[20:21], 0, v[18:19]
	v_lshl_add_u64 v[152:153], s[20:21], 0, v[22:23]
	v_or_b32_e32 v195, s7, v31
	s_add_i32 s23, s33, 4
	v_mul_lo_u32 v157, v146, s46
	v_mul_lo_u32 v160, v148, s46
	s_add_i32 s27, s22, s27
	s_or_b32 s33, s33, 3
	v_or_b32_e32 v165, 32, v163
	v_or_b32_e32 v166, 33, v163
	v_or_b32_e32 v167, 2, v163
	v_or_b32_e32 v168, 34, v163
	v_or_b32_e32 v169, 3, v163
	v_or_b32_e32 v170, 35, v163
	v_or_b32_e32 v171, 8, v163
	v_or_b32_e32 v172, 40, v163
	v_or_b32_e32 v173, 9, v163
	v_or_b32_e32 v174, 41, v163
	v_or_b32_e32 v175, 10, v163
	v_or_b32_e32 v176, 42, v163
	v_or_b32_e32 v177, 11, v163
	v_or_b32_e32 v178, 43, v163
	v_or_b32_e32 v179, 16, v163
	v_or_b32_e32 v180, 48, v163
	v_or_b32_e32 v181, 17, v163
	v_or_b32_e32 v182, 49, v163
	v_or_b32_e32 v183, 18, v163
	v_or_b32_e32 v184, 50, v163
	v_or_b32_e32 v185, 19, v163
	v_or_b32_e32 v186, 51, v163
	v_or_b32_e32 v187, 24, v163
	v_or_b32_e32 v188, 56, v163
	ds_write_b128 v26, v[2:5]
	v_mad_u64_u32 v[2:3], s[34:35], v146, 48, v[26:27]
	ds_write_b128 v2, v[6:9] offset:34816
	v_add_co_u32_e32 v2, vcc, s47, v20
	v_mov_b32_e32 v4, v1
	s_nop 0
	v_addc_co_u32_e32 v3, vcc, 0, v21, vcc
	global_load_dwordx4 v[130:133], v[2:3], off offset:-4096
	global_load_dwordx4 v[134:137], v[2:3], off
	v_add_co_u32_e32 v2, vcc, s47, v24
	v_mov_b32_e32 v5, v1
	s_nop 0
	v_addc_co_u32_e32 v3, vcc, 0, v25, vcc
	global_load_dwordx4 v[138:141], v[2:3], off offset:-4096
	global_load_dwordx4 v[142:145], v[2:3], off
	v_add3_u32 v2, 0, v158, v159
	v_mov_b32_e32 v6, v1
	v_mov_b32_e32 v7, v1
	v_mov_b32_e32 v8, v1
	v_mov_b32_e32 v9, v1
	v_or_b32_e32 v189, 25, v163
	v_or_b32_e32 v190, 57, v163
	v_or_b32_e32 v191, 26, v163
	v_or_b32_e32 v192, 58, v163
	v_or_b32_e32 v193, 27, v163
	v_or_b32_e32 v194, 59, v163
	ds_write_b128 v2, v[10:13]
	v_mad_u64_u32 v[2:3], s[34:35], v148, 48, v[2:3]
	ds_write_b128 v2, v[14:17] offset:34816
	v_lshrrev_b32_e32 v2, 2, v28
	v_and_or_b32 v0, v2, 3, v163
	v_lshlrev_b32_e32 v2, 1, v28
	v_lshlrev_b32_e32 v3, 3, v28
	v_mad_u32_u24 v0, v0, s46, 0
	v_and_b32_e32 v2, 32, v2
	v_and_b32_e32 v3, 24, v3
	v_mov_b32_e32 v14, v1
	v_mov_b32_e32 v15, v1
	v_add3_u32 v164, v0, v2, v3
	v_mov_b32_e32 v0, v1
	v_mov_b32_e32 v2, v1
	v_mov_b32_e32 v3, v1
	v_mov_b32_e32 v10, v1
	v_mov_b32_e32 v11, v1
	v_mov_b32_e32 v12, v1
	v_mov_b32_e32 v13, v1
	v_mov_b64_e32 v[64:65], v[14:15]
	v_mov_b64_e32 v[48:49], v[14:15]
	v_mov_b64_e32 v[32:33], v[14:15]
	v_mov_b64_e32 v[62:63], v[12:13]
	v_mov_b64_e32 v[60:61], v[10:11]
	v_mov_b64_e32 v[58:59], v[8:9]
	v_mov_b64_e32 v[56:57], v[6:7]
	v_mov_b64_e32 v[54:55], v[4:5]
	v_mov_b64_e32 v[52:53], v[2:3]
	v_mov_b64_e32 v[50:51], v[0:1]
	v_mov_b64_e32 v[46:47], v[12:13]
	v_mov_b64_e32 v[44:45], v[10:11]
	v_mov_b64_e32 v[42:43], v[8:9]
	v_mov_b64_e32 v[40:41], v[6:7]
	v_mov_b64_e32 v[38:39], v[4:5]
	v_mov_b64_e32 v[36:37], v[2:3]
	v_mov_b64_e32 v[34:35], v[0:1]
	v_mov_b64_e32 v[30:31], v[12:13]
	v_mov_b64_e32 v[28:29], v[10:11]
	v_mov_b64_e32 v[26:27], v[8:9]
	v_mov_b64_e32 v[24:25], v[6:7]
	v_mov_b64_e32 v[22:23], v[4:5]
	v_mov_b64_e32 v[20:21], v[2:3]
	v_mov_b64_e32 v[18:19], v[0:1]
	v_mov_b64_e32 v[16:17], v[14:15]
	v_mov_b64_e32 v[14:15], v[12:13]
	v_mov_b64_e32 v[12:13], v[10:11]
	v_mov_b64_e32 v[10:11], v[8:9]
	v_mov_b64_e32 v[8:9], v[6:7]
	v_mov_b64_e32 v[6:7], v[4:5]
	v_mov_b64_e32 v[4:5], v[2:3]
	v_mov_b64_e32 v[2:3], v[0:1]
	s_waitcnt lgkmcnt(0)
	s_movk_i32 s68, 0x5000
	s_mov_b32 s69, 0
	s_mov_b32 s70, 0xe800
	s_mov_b32 s72, 0
	s_barrier
	v_readfirstlane_b32 s73, v255
	s_cmp_lt_u32 s73, 0x100
	s_cbranch_scc1 .Lyp657
	s_setprio 1
.Lyp657:
	s_branch .LBB0_657
.LBB0_657:
	s_add_i32 s7, s25, -2
	s_and_b32 s7, s7, 1
	s_xor_b32 s20, s7, 1
	s_mul_i32 s21, s20, 0x4400
	s_add_i32 s21, s21, 0
	s_mulk_i32 s20, 0xc00
	s_add_i32 s20, s21, s20
	v_add3_u32 v0, s21, v149, v156
	s_waitcnt vmcnt(3)
	ds_write_b128 v0, v[130:133]
	v_add3_u32 v0, s68, v157, v156
	s_waitcnt vmcnt(2)
	ds_write_b128 v0, v[134:137] offset:34816
	v_add3_u32 v0, s21, v158, v159
	s_cmp_lt_u32 s25, s23
	s_waitcnt vmcnt(1)
	ds_write_b128 v0, v[138:141]
	v_add3_u32 v0, s68, v160, v159
	s_cselect_b32 s20, s25, s33
	s_lshl_b32 s20, s20, 6
	v_add_u32_e32 v250, s20, v146
	v_ashrrev_i32_e32 v251, 31, v250
	v_lshlrev_b64 v[250:251], 14, v[250:251]
	v_lshl_add_u64 v[250:251], v[150:151], 0, v[250:251]
	v_add_co_u32_e32 v252, vcc, s42, v250
	s_waitcnt vmcnt(0)
	ds_write_b128 v0, v[142:145] offset:34816
	v_addc_co_u32_e32 v253, vcc, 0, v251, vcc
	v_add_co_u32_e32 v250, vcc, 0x2000, v250
	s_nop 1
	v_addc_co_u32_e32 v251, vcc, 0, v251, vcc
	global_load_dwordx4 v[130:133], v[252:253], off
	global_load_dwordx4 v[134:137], v[250:251], off
	v_add_u32_e32 v250, s20, v148
	v_ashrrev_i32_e32 v251, 31, v250
	v_lshlrev_b64 v[250:251], 14, v[250:251]
	v_lshl_add_u64 v[250:251], v[152:153], 0, v[250:251]
	v_add_co_u32_e32 v252, vcc, 0x1000, v250
	s_sub_i32 s20, s26, 63
	s_nop 0
	v_addc_co_u32_e32 v253, vcc, 0, v251, vcc
	v_add_co_u32_e32 v250, vcc, 0x2000, v250
	s_cmp_gt_i32 s20, s27
	s_nop 0
	v_addc_co_u32_e32 v251, vcc, 0, v251, vcc
	global_load_dwordx4 v[138:141], v[252:253], off
	global_load_dwordx4 v[142:145], v[250:251], off
	s_sub_i32 s20, s26, 63
	s_cmp_gt_i32 s20, s27
	s_cbranch_scc1 .Lff2a_inact
	s_cmp_eq_u32 s72, 0
	s_cbranch_scc1 .Lff2a_first
	s_mul_i32 s20, s7, 0x4400
	v_add_u32_e32 v0, s20, v162
	ds_read_b128 v[198:201], v0
	ds_read_b128 v[202:205], v0 offset:32
	ds_read_b128 v[206:209], v0 offset:8704
	ds_read_b128 v[210:213], v0 offset:8736
	v_add_u32_e32 v246, s24, v161
	v_add_u32_e32 v234, 0x12800, v246
	v_add_u32_e32 v235, 0x12880, v246
	v_add_u32_e32 v238, 0x12820, v246
	v_add_u32_e32 v239, 0x128a0, v246
	v_add_u32_e32 v242, 0x12840, v246
	v_add_u32_e32 v243, 0x128c0, v246
	v_add_u32_e32 v247, 0x12860, v246
	v_add_u32_e32 v246, 0x128e0, v246
	ds_read_b128 v[218:221], v234
	ds_read_b128 v[234:237], v235
	ds_read_b128 v[222:225], v238
	ds_read_b128 v[238:241], v239
	ds_read_b128 v[226:229], v242
	ds_read_b128 v[242:245], v243
	ds_read_b128 v[230:233], v247
	ds_read_b128 v[246:249], v246
	s_waitcnt lgkmcnt(1)
	v_mfma_f32_32x32x16_bf16 v[218:233], v[198:201], v[98:101], v[218:233]
	v_sub_f32_e32 v82, v82, v197
	v_sub_f32_e32 v83, v83, v197
	v_sub_f32_e32 v84, v84, v197
	v_sub_f32_e32 v85, v85, v197
	v_exp_f32_e32 v82, v82
	v_exp_f32_e32 v83, v83
	v_exp_f32_e32 v84, v84
	v_exp_f32_e32 v85, v85
	s_waitcnt lgkmcnt(0)
	v_mfma_f32_32x32x16_bf16 v[234:249], v[206:209], v[98:101], v[234:249]
	v_sub_f32_e32 v86, v86, v197
	v_sub_f32_e32 v87, v87, v197
	v_sub_f32_e32 v88, v88, v197
	v_sub_f32_e32 v89, v89, v197
	v_exp_f32_e32 v86, v86
	v_exp_f32_e32 v87, v87
	v_exp_f32_e32 v88, v88
	v_exp_f32_e32 v89, v89
	v_mfma_f32_32x32x16_bf16 v[218:233], v[202:205], v[102:105], v[218:233]
	v_sub_f32_e32 v66, v66, v197
	v_sub_f32_e32 v67, v67, v197
	v_sub_f32_e32 v68, v68, v197
	v_sub_f32_e32 v69, v69, v197
	v_exp_f32_e32 v66, v66
	v_exp_f32_e32 v67, v67
	v_exp_f32_e32 v68, v68
	v_exp_f32_e32 v69, v69
	ds_read_b128 v[198:201], v0 offset:64
	ds_read_b128 v[202:205], v0 offset:96
	ds_read_b128 v[206:209], v0 offset:8768
	ds_read_b128 v[214:217], v0 offset:8800
	v_mfma_f32_32x32x16_bf16 v[234:249], v[210:213], v[102:105], v[234:249]
	v_add_f32_e32 v250, v82, v86
	v_add_f32_e32 v251, v83, v87
	v_add_f32_e32 v252, v84, v88
	v_add_f32_e32 v253, v85, v89
	v_sub_f32_e32 v70, v70, v197
	v_sub_f32_e32 v71, v71, v197
	v_sub_f32_e32 v72, v72, v197
	v_sub_f32_e32 v73, v73, v197
	s_waitcnt lgkmcnt(3)
	v_mfma_f32_32x32x16_bf16 v[218:233], v[198:201], v[106:109], v[218:233]
	v_exp_f32_e32 v70, v70
	v_exp_f32_e32 v71, v71
	v_exp_f32_e32 v72, v72
	v_exp_f32_e32 v73, v73
	v_add_f32_e32 v250, v250, v66
	v_add_f32_e32 v251, v251, v67
	v_add_f32_e32 v252, v252, v68
	v_add_f32_e32 v253, v253, v69
	s_waitcnt lgkmcnt(1)
	v_mfma_f32_32x32x16_bf16 v[234:249], v[206:209], v[106:109], v[234:249]
	v_sub_f32_e32 v90, v90, v197
	v_sub_f32_e32 v91, v91, v197
	v_sub_f32_e32 v92, v92, v197
	v_sub_f32_e32 v93, v93, v197
	v_exp_f32_e32 v90, v90
	v_exp_f32_e32 v91, v91
	v_exp_f32_e32 v92, v92
	v_exp_f32_e32 v93, v93
	v_mfma_f32_32x32x16_bf16 v[218:233], v[202:205], v[110:113], v[218:233]
	v_add_f32_e32 v250, v250, v70
	v_add_f32_e32 v251, v251, v71
	v_add_f32_e32 v252, v252, v72
	v_add_f32_e32 v253, v253, v73
	v_sub_f32_e32 v94, v94, v197
	v_sub_f32_e32 v95, v95, v197
	v_sub_f32_e32 v96, v96, v197
	v_sub_f32_e32 v97, v97, v197
	ds_read_b128 v[198:201], v0 offset:128
	ds_read_b128 v[202:205], v0 offset:160
	ds_read_b128 v[206:209], v0 offset:8832
	ds_read_b128 v[210:213], v0 offset:8864
	s_waitcnt lgkmcnt(4)
	v_mfma_f32_32x32x16_bf16 v[234:249], v[214:217], v[110:113], v[234:249]
	v_exp_f32_e32 v94, v94
	v_exp_f32_e32 v95, v95
	v_exp_f32_e32 v96, v96
	v_exp_f32_e32 v97, v97
	v_add_f32_e32 v250, v250, v90
	v_add_f32_e32 v251, v251, v91
	v_add_f32_e32 v252, v252, v92
	v_add_f32_e32 v253, v253, v93
	s_waitcnt lgkmcnt(3)
	v_mfma_f32_32x32x16_bf16 v[218:233], v[198:201], v[114:117], v[218:233]
	v_sub_f32_e32 v74, v74, v197
	v_sub_f32_e32 v75, v75, v197
	v_sub_f32_e32 v76, v76, v197
	v_sub_f32_e32 v77, v77, v197
	v_exp_f32_e32 v74, v74
	v_exp_f32_e32 v75, v75
	v_exp_f32_e32 v76, v76
	v_exp_f32_e32 v77, v77
	s_waitcnt lgkmcnt(1)
	v_mfma_f32_32x32x16_bf16 v[234:249], v[206:209], v[114:117], v[234:249]
	v_add_f32_e32 v250, v250, v94
	v_add_f32_e32 v251, v251, v95
	v_add_f32_e32 v252, v252, v96
	v_add_f32_e32 v253, v253, v97
	v_sub_f32_e32 v78, v78, v197
	v_sub_f32_e32 v79, v79, v197
	v_sub_f32_e32 v80, v80, v197
	v_sub_f32_e32 v81, v81, v197
	v_mfma_f32_32x32x16_bf16 v[218:233], v[202:205], v[118:121], v[218:233]
	v_exp_f32_e32 v78, v78
	v_exp_f32_e32 v79, v79
	v_exp_f32_e32 v80, v80
	v_exp_f32_e32 v81, v81
	v_add_f32_e32 v250, v250, v74
	v_add_f32_e32 v251, v251, v75
	v_add_f32_e32 v252, v252, v76
	v_add_f32_e32 v253, v253, v77
	ds_read_b128 v[198:201], v0 offset:192
	ds_read_b128 v[202:205], v0 offset:224
	ds_read_b128 v[206:209], v0 offset:8896
	ds_read_b128 v[214:217], v0 offset:8928
	s_waitcnt lgkmcnt(4)
	v_mfma_f32_32x32x16_bf16 v[234:249], v[210:213], v[118:121], v[234:249]
	v_add_f32_e32 v250, v250, v78
	v_add_f32_e32 v251, v251, v79
	v_add_f32_e32 v252, v252, v80
	v_add_f32_e32 v253, v253, v81
	v_add_f32_e32 v250, v250, v251
	v_add_f32_e32 v252, v252, v253
	v_add_f32_e32 v250, v250, v252
	v_add_f32_e32 v196, v196, v250
	s_waitcnt lgkmcnt(3)
	v_mfma_f32_32x32x16_bf16 v[218:233], v[198:201], v[122:125], v[218:233]
	v_cvt_pk_bf16_f32 v73, v72, v73
	v_cvt_pk_bf16_f32 v72, v70, v71
	v_cvt_pk_bf16_f32 v71, v68, v69
	v_cvt_pk_bf16_f32 v70, v66, v67
	v_cvt_pk_bf16_f32 v66, v82, v83
	v_cvt_pk_bf16_f32 v67, v84, v85
	v_cvt_pk_bf16_f32 v68, v86, v87
	v_cvt_pk_bf16_f32 v69, v88, v89
	s_waitcnt lgkmcnt(1)
	v_mfma_f32_32x32x16_bf16 v[234:249], v[206:209], v[122:125], v[234:249]
	v_cvt_pk_bf16_f32 v81, v80, v81
	v_cvt_pk_bf16_f32 v80, v78, v79
	v_cvt_pk_bf16_f32 v79, v76, v77
	v_cvt_pk_bf16_f32 v78, v74, v75
	v_cvt_pk_bf16_f32 v74, v90, v91
	v_cvt_pk_bf16_f32 v75, v92, v93
	v_cvt_pk_bf16_f32 v76, v94, v95
	v_cvt_pk_bf16_f32 v77, v96, v97
	v_mfma_f32_32x32x16_bf16 v[218:233], v[202:205], v[126:129], v[218:233]
	s_waitcnt lgkmcnt(0)
	v_mfma_f32_32x32x16_bf16 v[234:249], v[214:217], v[126:129], v[234:249]
	s_cmp_le_i32 s26, s27
	s_cbranch_scc1 .Lff2a_z2
	v_cmp_le_i32_e32 vcc, v165, v195
	s_nop 8
	v_cndmask_b32_e32 v234, v155, v234, vcc
	v_cmp_lt_i32_e32 vcc, v163, v195
	s_nop 1
	v_cndmask_b32_e32 v219, v155, v219, vcc
	v_cmp_le_i32_e32 vcc, v163, v195
	s_nop 1
	v_cndmask_b32_e32 v218, v155, v218, vcc
	v_cmp_le_i32_e32 vcc, v166, v195
	s_nop 1
	v_cndmask_b32_e32 v235, v155, v235, vcc
	v_cmp_le_i32_e32 vcc, v167, v195
	s_nop 1
	v_cndmask_b32_e32 v220, v155, v220, vcc
	v_cmp_le_i32_e32 vcc, v168, v195
	s_nop 1
	v_cndmask_b32_e32 v236, v155, v236, vcc
	v_cmp_le_i32_e32 vcc, v169, v195
	s_nop 1
	v_cndmask_b32_e32 v221, v155, v221, vcc
	v_cmp_le_i32_e32 vcc, v170, v195
	s_nop 1
	v_cndmask_b32_e32 v237, v155, v237, vcc
	v_cmp_le_i32_e32 vcc, v171, v195
	s_nop 1
	v_cndmask_b32_e32 v222, v155, v222, vcc
	v_cmp_le_i32_e32 vcc, v172, v195
	s_nop 1
	v_cndmask_b32_e32 v238, v155, v238, vcc
	v_cmp_le_i32_e32 vcc, v173, v195
	s_nop 1
	v_cndmask_b32_e32 v223, v155, v223, vcc
	v_cmp_le_i32_e32 vcc, v174, v195
	s_nop 1
	v_cndmask_b32_e32 v239, v155, v239, vcc
	v_cmp_le_i32_e32 vcc, v175, v195
	s_nop 1
	v_cndmask_b32_e32 v224, v155, v224, vcc
	v_cmp_le_i32_e32 vcc, v176, v195
	s_nop 1
	v_cndmask_b32_e32 v240, v155, v240, vcc
	v_cmp_le_i32_e32 vcc, v177, v195
	s_nop 1
	v_cndmask_b32_e32 v225, v155, v225, vcc
	v_cmp_le_i32_e32 vcc, v178, v195
	s_nop 1
	v_cndmask_b32_e32 v241, v155, v241, vcc
	v_cmp_le_i32_e32 vcc, v179, v195
	s_nop 1
	v_cndmask_b32_e32 v226, v155, v226, vcc
	v_cmp_le_i32_e32 vcc, v180, v195
	s_nop 1
	v_cndmask_b32_e32 v242, v155, v242, vcc
	v_cmp_le_i32_e32 vcc, v181, v195
	s_nop 1
	v_cndmask_b32_e32 v227, v155, v227, vcc
	v_cmp_le_i32_e32 vcc, v182, v195
	s_nop 1
	v_cndmask_b32_e32 v243, v155, v243, vcc
	v_cmp_le_i32_e32 vcc, v183, v195
	s_nop 1
	v_cndmask_b32_e32 v228, v155, v228, vcc
	v_cmp_le_i32_e32 vcc, v184, v195
	s_nop 1
	v_cndmask_b32_e32 v244, v155, v244, vcc
	v_cmp_le_i32_e32 vcc, v185, v195
	s_nop 1
	v_cndmask_b32_e32 v229, v155, v229, vcc
	v_cmp_le_i32_e32 vcc, v186, v195
	s_nop 1
	v_cndmask_b32_e32 v245, v155, v245, vcc
	v_cmp_le_i32_e32 vcc, v187, v195
	s_nop 1
	v_cndmask_b32_e32 v230, v155, v230, vcc
	v_cmp_le_i32_e32 vcc, v188, v195
	s_nop 1
	v_cndmask_b32_e32 v246, v155, v246, vcc
	v_cmp_le_i32_e32 vcc, v189, v195
	s_nop 1
	v_cndmask_b32_e32 v231, v155, v231, vcc
	v_cmp_le_i32_e32 vcc, v190, v195
	s_nop 1
	v_cndmask_b32_e32 v247, v155, v247, vcc
	v_cmp_le_i32_e32 vcc, v191, v195
	s_nop 1
	v_cndmask_b32_e32 v232, v155, v232, vcc
	v_cmp_le_i32_e32 vcc, v192, v195
	s_nop 1
	v_cndmask_b32_e32 v248, v155, v248, vcc
	v_cmp_le_i32_e32 vcc, v193, v195
	s_nop 1
	v_cndmask_b32_e32 v233, v155, v233, vcc
	v_cmp_le_i32_e32 vcc, v194, v195
	s_nop 1
	v_cndmask_b32_e32 v249, v155, v249, vcc
